# EpiFFN packed-pair math, two pair blocks interleaved for ILP
# speedup vs baseline: 1.0053x; 1.0053x over previous
.LBB0_1404:
	s_add_u32 s16, s10, 0xfffc0080
	s_addc_u32 s17, s11, -1
	s_add_i32 s41, 0, 0x10000
	v_add_u32_e32 v132, s41, v198
	ds_read_b128 v[116:119], v132
	ds_read_b128 v[124:127], v132 offset:1024
	ds_read_b128 v[128:131], v132 offset:2048
	ds_read_b128 v[132:135], v132 offset:3072
	s_cmp_eq_u32 s40, 12
	s_cselect_b32 s35, s6, s17
	s_cselect_b32 s34, s31, s16
	s_cselect_b32 s17, s5, s39
	s_cselect_b32 s16, s36, s37
	v_lshl_add_u64 v[186:187], s[10:11], 0, v[176:177]
	s_add_i32 m0, s33, 0xc000
	ds_read_b128 v[136:139], v199
	ds_read_b128 v[140:143], v199 offset:1024
	ds_read_b128 v[144:147], v199 offset:2048
	ds_read_b128 v[148:151], v199 offset:3072
	ds_read_b128 v[152:155], v199 offset:4096
	ds_read_b128 v[178:181], v199 offset:5120
	ds_read_b128 v[182:185], v199 offset:6144
	ds_read_b128 v[200:203], v199 offset:7168
	global_load_lds_dwordx4 v[186:187], off
	v_lshl_add_u64 v[186:187], s[10:11], 0, v[174:175]
	s_add_i32 m0, s33, 0xe000
	s_nop 0
	global_load_lds_dwordx4 v[186:187], off
	s_waitcnt lgkmcnt(8)
	s_barrier
	s_waitcnt lgkmcnt(0)
	s_setprio 1
	s_waitcnt lgkmcnt(0)
	v_mfma_f32_16x16x32_bf16 v[160:163], v[116:119], v[136:139], v[160:163]
	v_mfma_f32_16x16x32_bf16 v[60:63], v[128:131], v[136:139], v[60:63]
	v_mfma_f32_16x16x32_bf16 v[120:123], v[116:119], v[144:147], v[120:123]
	v_mfma_f32_16x16x32_bf16 v[52:55], v[128:131], v[144:147], v[52:55]
	v_mfma_f32_16x16x32_bf16 v[108:111], v[116:119], v[152:155], v[108:111]
	v_mfma_f32_16x16x32_bf16 v[44:47], v[128:131], v[152:155], v[44:47]
	v_mfma_f32_16x16x32_bf16 v[100:103], v[116:119], v[182:185], v[100:103]
	v_mfma_f32_16x16x32_bf16 v[36:39], v[128:131], v[182:185], v[36:39]
	v_mfma_f32_16x16x32_bf16 v[160:163], v[124:127], v[140:143], v[160:163]
	v_mfma_f32_16x16x32_bf16 v[60:63], v[132:135], v[140:143], v[60:63]
	v_mfma_f32_16x16x32_bf16 v[120:123], v[124:127], v[148:151], v[120:123]
	v_mfma_f32_16x16x32_bf16 v[52:55], v[132:135], v[148:151], v[52:55]
	v_mfma_f32_16x16x32_bf16 v[108:111], v[124:127], v[178:181], v[108:111]
	v_mfma_f32_16x16x32_bf16 v[44:47], v[132:135], v[178:181], v[44:47]
	v_mfma_f32_16x16x32_bf16 v[100:103], v[124:127], v[200:203], v[100:103]
	v_mfma_f32_16x16x32_bf16 v[36:39], v[132:135], v[200:203], v[36:39]
	s_setprio 0
	s_barrier
	s_add_i32 s48, 0, 0x14000
	s_add_i32 s41, s41, s27
	v_add_u32_e32 v164, s48, v198
	v_lshl_add_u64 v[186:187], s[16:17], 0, v[172:173]
	s_mov_b32 m0, s41
	ds_read_b128 v[204:207], v164
	ds_read_b128 v[208:211], v164 offset:1024
	ds_read_b128 v[212:215], v164 offset:2048
	ds_read_b128 v[216:219], v164 offset:3072
	global_load_lds_dwordx4 v[186:187], off
	v_lshl_add_u64 v[186:187], s[16:17], 0, v[168:169]
	s_add_i32 m0, s41, 0x2000
	s_nop 0
	global_load_lds_dwordx4 v[186:187], off
	s_barrier
	s_waitcnt lgkmcnt(0)
	s_setprio 1
	s_waitcnt lgkmcnt(0)
	v_mfma_f32_16x16x32_bf16 v[156:159], v[204:207], v[136:139], v[156:159]
	v_mfma_f32_16x16x32_bf16 v[56:59], v[212:215], v[136:139], v[56:59]
	v_mfma_f32_16x16x32_bf16 v[112:115], v[204:207], v[144:147], v[112:115]
	v_mfma_f32_16x16x32_bf16 v[48:51], v[212:215], v[144:147], v[48:51]
	v_mfma_f32_16x16x32_bf16 v[104:107], v[204:207], v[152:155], v[104:107]
	v_mfma_f32_16x16x32_bf16 v[40:43], v[212:215], v[152:155], v[40:43]
	v_mfma_f32_16x16x32_bf16 v[96:99], v[204:207], v[182:185], v[96:99]
	v_mfma_f32_16x16x32_bf16 v[32:35], v[212:215], v[182:185], v[32:35]
	v_mfma_f32_16x16x32_bf16 v[156:159], v[208:211], v[140:143], v[156:159]
	v_mfma_f32_16x16x32_bf16 v[56:59], v[216:219], v[140:143], v[56:59]
	v_mfma_f32_16x16x32_bf16 v[112:115], v[208:211], v[148:151], v[112:115]
	v_mfma_f32_16x16x32_bf16 v[48:51], v[216:219], v[148:151], v[48:51]
	v_mfma_f32_16x16x32_bf16 v[104:107], v[208:211], v[178:181], v[104:107]
	v_mfma_f32_16x16x32_bf16 v[40:43], v[216:219], v[178:181], v[40:43]
	v_mfma_f32_16x16x32_bf16 v[96:99], v[208:211], v[200:203], v[96:99]
	v_mfma_f32_16x16x32_bf16 v[32:35], v[216:219], v[200:203], v[32:35]
	s_setprio 0
	s_mov_b32 m0, s33
	v_lshl_add_u64 v[186:187], s[34:35], 0, v[170:171]
	s_barrier
	ds_read_b128 v[136:139], v199 offset:16384
	ds_read_b128 v[140:143], v199 offset:17408
	ds_read_b128 v[144:147], v199 offset:18432
	ds_read_b128 v[148:151], v199 offset:19456
	ds_read_b128 v[152:155], v199 offset:20480
	ds_read_b128 v[178:181], v199 offset:21504
	ds_read_b128 v[182:185], v199 offset:22528
	ds_read_b128 v[200:203], v199 offset:23552
	global_load_lds_dwordx4 v[186:187], off
	v_lshl_add_u64 v[220:221], s[34:35], 0, v[166:167]
	s_mov_b32 m0, s2
	s_nop 0
	global_load_lds_dwordx4 v[220:221], off
	s_barrier
	s_waitcnt lgkmcnt(0)
	s_setprio 1
	s_waitcnt lgkmcnt(0)
	v_mfma_f32_16x16x32_bf16 v[92:95], v[116:119], v[136:139], v[92:95]
	v_mfma_f32_16x16x32_bf16 v[28:31], v[128:131], v[136:139], v[28:31]
	v_mfma_f32_16x16x32_bf16 v[84:87], v[116:119], v[144:147], v[84:87]
	v_mfma_f32_16x16x32_bf16 v[20:23], v[128:131], v[144:147], v[20:23]
	v_mfma_f32_16x16x32_bf16 v[76:79], v[116:119], v[152:155], v[76:79]
	v_mfma_f32_16x16x32_bf16 v[12:15], v[128:131], v[152:155], v[12:15]
	v_mfma_f32_16x16x32_bf16 v[68:71], v[116:119], v[182:185], v[68:71]
	v_mfma_f32_16x16x32_bf16 v[4:7], v[128:131], v[182:185], v[4:7]
	v_mfma_f32_16x16x32_bf16 v[92:95], v[124:127], v[140:143], v[92:95]
	v_mfma_f32_16x16x32_bf16 v[28:31], v[132:135], v[140:143], v[28:31]
	v_mfma_f32_16x16x32_bf16 v[84:87], v[124:127], v[148:151], v[84:87]
	v_mfma_f32_16x16x32_bf16 v[20:23], v[132:135], v[148:151], v[20:23]
	v_mfma_f32_16x16x32_bf16 v[76:79], v[124:127], v[178:181], v[76:79]
	v_mfma_f32_16x16x32_bf16 v[12:15], v[132:135], v[178:181], v[12:15]
	v_mfma_f32_16x16x32_bf16 v[68:71], v[124:127], v[200:203], v[68:71]
	v_mfma_f32_16x16x32_bf16 v[4:7], v[132:135], v[200:203], v[4:7]
	s_setprio 0
	s_barrier
	s_add_u32 s52, s16, 0x4000
	s_addc_u32 s53, s17, 0
	s_add_i32 s41, s48, s27
	v_lshl_add_u64 v[116:117], s[52:53], 0, v[172:173]
	s_mov_b32 m0, s41
	s_nop 0
	global_load_lds_dwordx4 v[116:117], off
	v_lshl_add_u64 v[116:117], s[52:53], 0, v[168:169]
	s_add_i32 m0, s41, 0x2000
	s_nop 0
	global_load_lds_dwordx4 v[116:117], off
	s_waitcnt vmcnt(6)
	s_barrier
	s_setprio 1
	v_mfma_f32_16x16x32_bf16 v[88:91], v[204:207], v[136:139], v[88:91]
	v_mfma_f32_16x16x32_bf16 v[24:27], v[212:215], v[136:139], v[24:27]
	v_mfma_f32_16x16x32_bf16 v[80:83], v[204:207], v[144:147], v[80:83]
	v_mfma_f32_16x16x32_bf16 v[16:19], v[212:215], v[144:147], v[16:19]
	v_mfma_f32_16x16x32_bf16 v[72:75], v[204:207], v[152:155], v[72:75]
	v_mfma_f32_16x16x32_bf16 v[8:11], v[212:215], v[152:155], v[8:11]
	v_mfma_f32_16x16x32_bf16 v[64:67], v[204:207], v[182:185], v[64:67]
	v_mfma_f32_16x16x32_bf16 v[0:3], v[212:215], v[182:185], v[0:3]
	v_mfma_f32_16x16x32_bf16 v[88:91], v[208:211], v[140:143], v[88:91]
	v_mfma_f32_16x16x32_bf16 v[24:27], v[216:219], v[140:143], v[24:27]
	v_mfma_f32_16x16x32_bf16 v[80:83], v[208:211], v[148:151], v[80:83]
	v_mfma_f32_16x16x32_bf16 v[16:19], v[216:219], v[148:151], v[16:19]
	v_mfma_f32_16x16x32_bf16 v[72:75], v[208:211], v[178:181], v[72:75]
	v_mfma_f32_16x16x32_bf16 v[8:11], v[216:219], v[178:181], v[8:11]
	v_mfma_f32_16x16x32_bf16 v[64:67], v[208:211], v[200:203], v[64:67]
	v_mfma_f32_16x16x32_bf16 v[0:3], v[216:219], v[200:203], v[0:3]
	s_setprio 0
	s_add_i32 s41, 0, 0x18000
	v_add_u32_e32 v132, s41, v198
	s_barrier
	ds_read_b128 v[116:119], v132
	ds_read_b128 v[124:127], v132 offset:1024
	ds_read_b128 v[128:131], v132 offset:2048
	ds_read_b128 v[132:135], v132 offset:3072
	s_add_u32 s34, s34, 0x40000
	s_addc_u32 s35, s35, 0
	s_mov_b32 m0, s78
	v_lshl_add_u64 v[204:205], s[34:35], 0, v[170:171]
	ds_read_b128 v[136:139], v199 offset:32768
	ds_read_b128 v[140:143], v199 offset:33792
	ds_read_b128 v[144:147], v199 offset:34816
	ds_read_b128 v[148:151], v199 offset:35840
	ds_read_b128 v[152:155], v199 offset:36864
	ds_read_b128 v[178:181], v199 offset:37888
	ds_read_b128 v[182:185], v199 offset:38912
	ds_read_b128 v[200:203], v199 offset:39936
	global_load_lds_dwordx4 v[204:205], off
	v_lshl_add_u64 v[204:205], s[34:35], 0, v[166:167]
	s_mov_b32 m0, s79
	s_nop 0
	global_load_lds_dwordx4 v[204:205], off
	s_waitcnt lgkmcnt(8)
	s_barrier
	s_waitcnt lgkmcnt(0)
	s_setprio 1
	s_waitcnt lgkmcnt(0)
	v_mfma_f32_16x16x32_bf16 v[160:163], v[116:119], v[136:139], v[160:163]
	v_mfma_f32_16x16x32_bf16 v[60:63], v[128:131], v[136:139], v[60:63]
	v_mfma_f32_16x16x32_bf16 v[120:123], v[116:119], v[144:147], v[120:123]
	v_mfma_f32_16x16x32_bf16 v[52:55], v[128:131], v[144:147], v[52:55]
	v_mfma_f32_16x16x32_bf16 v[108:111], v[116:119], v[152:155], v[108:111]
	v_mfma_f32_16x16x32_bf16 v[44:47], v[128:131], v[152:155], v[44:47]
	v_mfma_f32_16x16x32_bf16 v[100:103], v[116:119], v[182:185], v[100:103]
	v_mfma_f32_16x16x32_bf16 v[36:39], v[128:131], v[182:185], v[36:39]
	v_mfma_f32_16x16x32_bf16 v[160:163], v[124:127], v[140:143], v[160:163]
	v_mfma_f32_16x16x32_bf16 v[60:63], v[132:135], v[140:143], v[60:63]
	v_mfma_f32_16x16x32_bf16 v[120:123], v[124:127], v[148:151], v[120:123]
	v_mfma_f32_16x16x32_bf16 v[52:55], v[132:135], v[148:151], v[52:55]
	v_mfma_f32_16x16x32_bf16 v[108:111], v[124:127], v[178:181], v[108:111]
	v_mfma_f32_16x16x32_bf16 v[44:47], v[132:135], v[178:181], v[44:47]
	v_mfma_f32_16x16x32_bf16 v[100:103], v[124:127], v[200:203], v[100:103]
	v_mfma_f32_16x16x32_bf16 v[36:39], v[132:135], v[200:203], v[36:39]
	s_setprio 0
	s_barrier
	s_add_i32 s48, 0, 0x1c000
	s_add_u32 s34, s16, 0x8000
	s_addc_u32 s35, s17, 0
	s_add_i32 s41, s41, s27
	v_add_u32_e32 v164, s48, v198
	v_lshl_add_u64 v[222:223], s[34:35], 0, v[172:173]
	s_mov_b32 m0, s41
	ds_read_b128 v[204:207], v164
	ds_read_b128 v[208:211], v164 offset:1024
	ds_read_b128 v[212:215], v164 offset:2048
	ds_read_b128 v[216:219], v164 offset:3072
	global_load_lds_dwordx4 v[222:223], off
	v_lshl_add_u64 v[222:223], s[34:35], 0, v[168:169]
	s_add_i32 m0, s41, 0x2000
	s_nop 0
	global_load_lds_dwordx4 v[222:223], off
	s_barrier
	s_waitcnt lgkmcnt(0)
	s_setprio 1
	s_waitcnt lgkmcnt(0)
	v_mfma_f32_16x16x32_bf16 v[156:159], v[204:207], v[136:139], v[156:159]
	v_mfma_f32_16x16x32_bf16 v[56:59], v[212:215], v[136:139], v[56:59]
	v_mfma_f32_16x16x32_bf16 v[112:115], v[204:207], v[144:147], v[112:115]
	v_mfma_f32_16x16x32_bf16 v[48:51], v[212:215], v[144:147], v[48:51]
	v_mfma_f32_16x16x32_bf16 v[104:107], v[204:207], v[152:155], v[104:107]
	v_mfma_f32_16x16x32_bf16 v[40:43], v[212:215], v[152:155], v[40:43]
	v_mfma_f32_16x16x32_bf16 v[96:99], v[204:207], v[182:185], v[96:99]
	v_mfma_f32_16x16x32_bf16 v[32:35], v[212:215], v[182:185], v[32:35]
	v_mfma_f32_16x16x32_bf16 v[156:159], v[208:211], v[140:143], v[156:159]
	v_mfma_f32_16x16x32_bf16 v[56:59], v[216:219], v[140:143], v[56:59]
	v_mfma_f32_16x16x32_bf16 v[112:115], v[208:211], v[148:151], v[112:115]
	v_mfma_f32_16x16x32_bf16 v[48:51], v[216:219], v[148:151], v[48:51]
	v_mfma_f32_16x16x32_bf16 v[104:107], v[208:211], v[178:181], v[104:107]
	v_mfma_f32_16x16x32_bf16 v[40:43], v[216:219], v[178:181], v[40:43]
	v_mfma_f32_16x16x32_bf16 v[96:99], v[208:211], v[200:203], v[96:99]
	v_mfma_f32_16x16x32_bf16 v[32:35], v[216:219], v[200:203], v[32:35]
	s_setprio 0
	s_mov_b32 m0, s82
	v_lshl_add_u64 v[186:187], v[186:187], 0, s[18:19]
	s_barrier
	ds_read_b128 v[136:139], v199 offset:49152
	ds_read_b128 v[140:143], v199 offset:50176
	ds_read_b128 v[144:147], v199 offset:51200
	ds_read_b128 v[148:151], v199 offset:52224
	ds_read_b128 v[152:155], v199 offset:53248
	ds_read_b128 v[178:181], v199 offset:54272
	ds_read_b128 v[182:185], v199 offset:55296
	ds_read_b128 v[200:203], v199 offset:56320
	global_load_lds_dwordx4 v[186:187], off
	v_lshl_add_u64 v[186:187], v[220:221], 0, s[18:19]
	s_mov_b32 m0, s83
	s_nop 0
	global_load_lds_dwordx4 v[186:187], off
	s_barrier
	s_waitcnt lgkmcnt(0)
	s_setprio 1
	s_waitcnt lgkmcnt(0)
	v_mfma_f32_16x16x32_bf16 v[92:95], v[116:119], v[136:139], v[92:95]
	v_mfma_f32_16x16x32_bf16 v[28:31], v[128:131], v[136:139], v[28:31]
	v_mfma_f32_16x16x32_bf16 v[84:87], v[116:119], v[144:147], v[84:87]
	v_mfma_f32_16x16x32_bf16 v[20:23], v[128:131], v[144:147], v[20:23]
	v_mfma_f32_16x16x32_bf16 v[76:79], v[116:119], v[152:155], v[76:79]
	v_mfma_f32_16x16x32_bf16 v[12:15], v[128:131], v[152:155], v[12:15]
	v_mfma_f32_16x16x32_bf16 v[68:71], v[116:119], v[182:185], v[68:71]
	v_mfma_f32_16x16x32_bf16 v[4:7], v[128:131], v[182:185], v[4:7]
	v_mfma_f32_16x16x32_bf16 v[92:95], v[124:127], v[140:143], v[92:95]
	v_mfma_f32_16x16x32_bf16 v[28:31], v[132:135], v[140:143], v[28:31]
	v_mfma_f32_16x16x32_bf16 v[84:87], v[124:127], v[148:151], v[84:87]
	v_mfma_f32_16x16x32_bf16 v[20:23], v[132:135], v[148:151], v[20:23]
	v_mfma_f32_16x16x32_bf16 v[76:79], v[124:127], v[178:181], v[76:79]
	v_mfma_f32_16x16x32_bf16 v[12:15], v[132:135], v[178:181], v[12:15]
	v_mfma_f32_16x16x32_bf16 v[68:71], v[124:127], v[200:203], v[68:71]
	v_mfma_f32_16x16x32_bf16 v[4:7], v[132:135], v[200:203], v[4:7]
	s_setprio 0
	s_barrier
	s_add_u32 s16, s16, 0xc000
	s_addc_u32 s17, s17, 0
	s_add_i32 s34, s48, s27
	v_lshl_add_u64 v[116:117], s[16:17], 0, v[172:173]
	s_mov_b32 m0, s34
	s_nop 0
	global_load_lds_dwordx4 v[116:117], off
	v_lshl_add_u64 v[116:117], s[16:17], 0, v[168:169]
	s_add_i32 m0, s34, 0x2000
	s_nop 0
	global_load_lds_dwordx4 v[116:117], off
	s_waitcnt vmcnt(6)
	s_barrier
	s_setprio 1
	v_mfma_f32_16x16x32_bf16 v[88:91], v[204:207], v[136:139], v[88:91]
	v_mfma_f32_16x16x32_bf16 v[24:27], v[212:215], v[136:139], v[24:27]
	v_mfma_f32_16x16x32_bf16 v[80:83], v[204:207], v[144:147], v[80:83]
	v_mfma_f32_16x16x32_bf16 v[16:19], v[212:215], v[144:147], v[16:19]
	v_mfma_f32_16x16x32_bf16 v[72:75], v[204:207], v[152:155], v[72:75]
	v_mfma_f32_16x16x32_bf16 v[8:11], v[212:215], v[152:155], v[8:11]
	v_mfma_f32_16x16x32_bf16 v[64:67], v[204:207], v[182:185], v[64:67]
	v_mfma_f32_16x16x32_bf16 v[0:3], v[212:215], v[182:185], v[0:3]
	v_mfma_f32_16x16x32_bf16 v[88:91], v[208:211], v[140:143], v[88:91]
	v_mfma_f32_16x16x32_bf16 v[24:27], v[216:219], v[140:143], v[24:27]
	v_mfma_f32_16x16x32_bf16 v[80:83], v[208:211], v[148:151], v[80:83]
	v_mfma_f32_16x16x32_bf16 v[16:19], v[216:219], v[148:151], v[16:19]
	v_mfma_f32_16x16x32_bf16 v[72:75], v[208:211], v[178:181], v[72:75]
	v_mfma_f32_16x16x32_bf16 v[8:11], v[216:219], v[178:181], v[8:11]
	v_mfma_f32_16x16x32_bf16 v[64:67], v[208:211], v[200:203], v[64:67]
	v_mfma_f32_16x16x32_bf16 v[0:3], v[216:219], v[200:203], v[0:3]
	s_setprio 0
	s_add_i32 s40, s40, 2
	s_add_u32 s37, s37, 0x10000
	s_addc_u32 s39, s39, 0
	s_add_u32 s10, s10, 0x100
	s_addc_u32 s11, s11, 0
	s_cmp_gt_u32 s40, 13
	s_barrier
	s_cbranch_scc0 .LBB0_1404
	v_mov_b32_e32 v116, v188
	s_lshl_b32 s6, s38, 7
	v_readfirstlane_b32 s10, v116
	s_lshr_b32 s5, s10, 1
	v_and_b32_e32 v200, 15, v116
	s_and_b32 s5, s5, 0x60
	v_lshrrev_b32_e32 v116, 1, v116
	s_or_b32 s6, s5, s6
	v_and_b32_e32 v116, 24, v116
	v_or_b32_e32 v182, s6, v116
	v_ashrrev_i32_e32 v183, 31, v182
	v_lshlrev_b64 v[118:119], 2, v[182:183]
	v_lshl_add_u64 v[184:185], s[42:43], 0, v[118:119]
	global_load_dwordx4 v[124:127], v[184:185], off
	v_lshl_add_u64 v[128:129], s[58:59], 0, v[118:119]
	global_load_dwordx4 v[128:131], v[128:129], off
	v_lshl_add_u64 v[132:133], s[60:61], 0, v[118:119]
	global_load_dwordx4 v[132:135], v[132:133], off
	v_lshl_add_u64 v[186:187], s[46:47], 0, v[118:119]
	global_load_dwordx4 v[136:139], v[186:187], off
	v_lshl_add_u64 v[140:141], s[12:13], 0, v[118:119]
	global_load_dwordx4 v[140:143], v[140:141], off
	v_lshl_add_u64 v[144:145], s[50:51], 0, v[118:119]
	global_load_dwordx4 v[144:147], v[144:145], off
	v_lshl_add_u64 v[148:149], s[20:21], 0, v[118:119]
	global_load_dwordx4 v[148:151], v[148:149], off
	v_lshl_add_u64 v[118:119], s[44:45], 0, v[118:119]
	global_load_dwordx4 v[152:155], v[118:119], off
	v_mov_b32_e32 v254, 0xbfb8aa3b
	v_mov_b32_e32 v255, 0xbfb8aa3b
	v_mov_b32_e32 v252, 1.0
	v_mov_b32_e32 v253, 1.0
	v_cmp_eq_u32_e32 vcc, 15, v200
	v_cmp_eq_u32_e64 s[34:35], 0, v200
	s_nop 0
	s_nop 0
	v_mov_b32_e32 v180, v165
	s_lshl_b32 s11, s7, 8
	s_ashr_i32 s7, s10, 2
	s_andn2_b32 s7, s7, 63
	s_add_i32 s31, s7, s11
	v_mov_b32_e32 v181, v165
	s_ashr_i32 s10, s31, 6
	s_ashr_i32 s11, s10, 31
	s_lshl_b32 s16, s38, 8
	s_lshl_b64 s[52:53], s[10:11], 2
	v_cmp_gt_u32_e64 s[36:37], 2, v200
	s_ashr_i32 s17, s16, 31
	v_or_b32_e32 v183, s52, v200
	s_waitcnt vmcnt(0)
	v_cndmask_b32_e64 v204, v160, 0, vcc
	v_cndmask_b32_e64 v214, v162, 0, vcc
	v_cndmask_b32_e64 v205, v161, 0, vcc
	v_cndmask_b32_e64 v215, v163, 0, vcc
	v_cndmask_b32_e64 v206, v156, 0, vcc
	v_cndmask_b32_e64 v220, v158, 0, vcc
	v_cndmask_b32_e64 v207, v157, 0, vcc
	v_cndmask_b32_e64 v221, v159, 0, vcc
	v_pk_fma_f32 v[208:209], v[160:161], v[128:129], v[136:137]
	v_pk_fma_f32 v[222:223], v[162:163], v[130:131], v[138:139]
	v_pk_fma_f32 v[210:211], v[156:157], v[144:145], v[152:153]
	v_pk_fma_f32 v[240:241], v[158:159], v[146:147], v[154:155]
	v_fmac_f32_dpp v208, v204, v124 row_ror:1 row_mask:0xf bank_mask:0xf bound_ctrl:1
	v_fmac_f32_dpp v222, v214, v126 row_ror:1 row_mask:0xf bank_mask:0xf bound_ctrl:1
	v_fmac_f32_dpp v209, v205, v125 row_ror:1 row_mask:0xf bank_mask:0xf bound_ctrl:1
	v_fmac_f32_dpp v223, v215, v127 row_ror:1 row_mask:0xf bank_mask:0xf bound_ctrl:1
	v_fmac_f32_dpp v210, v206, v140 row_ror:1 row_mask:0xf bank_mask:0xf bound_ctrl:1
	v_fmac_f32_dpp v240, v220, v142 row_ror:1 row_mask:0xf bank_mask:0xf bound_ctrl:1
	v_fmac_f32_dpp v211, v207, v141 row_ror:1 row_mask:0xf bank_mask:0xf bound_ctrl:1
	v_fmac_f32_dpp v241, v221, v143 row_ror:1 row_mask:0xf bank_mask:0xf bound_ctrl:1
	v_cndmask_b32_e64 v204, v160, v120, s[34:35]
	v_cndmask_b32_e64 v214, v162, v122, s[34:35]
	v_cndmask_b32_e64 v205, v161, v121, s[34:35]
	v_cndmask_b32_e64 v215, v163, v123, s[34:35]
	v_cndmask_b32_e64 v206, v156, v112, s[34:35]
	v_cndmask_b32_e64 v220, v158, v114, s[34:35]
	v_cndmask_b32_e64 v207, v157, v113, s[34:35]
	v_cndmask_b32_e64 v221, v159, v115, s[34:35]
	v_fmac_f32_dpp v208, v204, v132 row_ror:15 row_mask:0xf bank_mask:0xf
	v_fmac_f32_dpp v222, v214, v134 row_ror:15 row_mask:0xf bank_mask:0xf
	v_fmac_f32_dpp v209, v205, v133 row_ror:15 row_mask:0xf bank_mask:0xf
	v_fmac_f32_dpp v223, v215, v135 row_ror:15 row_mask:0xf bank_mask:0xf
	v_fmac_f32_dpp v210, v206, v148 row_ror:15 row_mask:0xf bank_mask:0xf
	v_fmac_f32_dpp v240, v220, v150 row_ror:15 row_mask:0xf bank_mask:0xf
	v_fmac_f32_dpp v211, v207, v149 row_ror:15 row_mask:0xf bank_mask:0xf
	v_fmac_f32_dpp v241, v221, v151 row_ror:15 row_mask:0xf bank_mask:0xf
	v_pk_mul_f32 v[212:213], v[254:255], v[208:209]
	v_pk_mul_f32 v[242:243], v[254:255], v[222:223]
	v_exp_f32_e32 v212, v212
	v_exp_f32_e32 v242, v242
	v_exp_f32_e32 v213, v213
	v_exp_f32_e32 v243, v243
	v_pk_add_f32 v[212:213], v[212:213], v[252:253]
	v_pk_add_f32 v[242:243], v[242:243], v[252:253]
	v_rcp_f32_e32 v212, v212
	v_rcp_f32_e32 v242, v242
	v_rcp_f32_e32 v213, v213
	v_rcp_f32_e32 v243, v243
	v_pk_mul_f32 v[208:209], v[208:209], v[212:213]
	v_pk_mul_f32 v[222:223], v[222:223], v[242:243]
	v_pk_mul_f32 v[210:211], v[210:211], v[208:209]
	v_pk_mul_f32 v[240:241], v[240:241], v[222:223]
	s_nop 1
	s_nop 0
	v_cvt_pk_bf16_f32 v118, v210, v211
	v_lshlrev_b32_e32 v178, 1, v116
	v_cvt_pk_bf16_f32 v119, v240, v241
	s_and_saveexec_b64 s[10:11], s[36:37]
	s_cbranch_execz .LBB0_1407
	v_mov_b64_e32 v[116:117], s[0:1]
	v_mad_i64_i32 v[116:117], s[38:39], v183, s66, v[116:117]
	v_lshl_add_u64 v[116:117], s[16:17], 1, v[116:117]
	s_lshl_b32 s48, s5, 1
	v_lshl_add_u64 v[116:117], v[116:117], 0, s[48:49]
	v_mov_b32_e32 v179, v165
	v_lshl_add_u64 v[116:117], v[116:117], 0, v[178:179]
	v_cvt_pk_bf16_f32 v180, v160, v161
	v_cvt_pk_bf16_f32 v181, v162, v163
	global_store_dwordx2 v[116:117], v[180:181], off
	v_cvt_pk_bf16_f32 v180, v156, v157
	v_cvt_pk_bf16_f32 v181, v158, v159
	global_store_dwordx2 v[116:117], v[180:181], off offset:256
.LBB0_1407:
	s_or_b64 exec, exec, s[10:11]
	v_cndmask_b32_e64 v244, v120, v160, vcc
	v_cndmask_b32_e64 v206, v108, v120, vcc
	v_cndmask_b32_e64 v245, v121, v161, vcc
	v_cndmask_b32_e64 v207, v109, v121, vcc
	v_cndmask_b32_e64 v246, v112, v156, vcc
	v_cndmask_b32_e64 v208, v104, v112, vcc
	v_cndmask_b32_e64 v247, v113, v157, vcc
	v_cndmask_b32_e64 v209, v105, v113, vcc
	v_pk_fma_f32 v[248:249], v[120:121], v[128:129], v[136:137]
	v_pk_fma_f32 v[212:213], v[108:109], v[128:129], v[136:137]
	v_pk_fma_f32 v[250:251], v[112:113], v[144:145], v[152:153]
	v_pk_fma_f32 v[214:215], v[104:105], v[144:145], v[152:153]
	v_fmac_f32_dpp v248, v244, v124 row_ror:1 row_mask:0xf bank_mask:0xf bound_ctrl:1
	v_fmac_f32_dpp v212, v206, v124 row_ror:1 row_mask:0xf bank_mask:0xf bound_ctrl:1
	v_fmac_f32_dpp v249, v245, v125 row_ror:1 row_mask:0xf bank_mask:0xf bound_ctrl:1
	v_fmac_f32_dpp v213, v207, v125 row_ror:1 row_mask:0xf bank_mask:0xf bound_ctrl:1
	v_fmac_f32_dpp v250, v246, v140 row_ror:1 row_mask:0xf bank_mask:0xf bound_ctrl:1
	v_fmac_f32_dpp v214, v208, v140 row_ror:1 row_mask:0xf bank_mask:0xf bound_ctrl:1
	v_fmac_f32_dpp v251, v247, v141 row_ror:1 row_mask:0xf bank_mask:0xf bound_ctrl:1
	v_fmac_f32_dpp v215, v209, v141 row_ror:1 row_mask:0xf bank_mask:0xf bound_ctrl:1
	v_cndmask_b32_e64 v244, v120, v108, s[34:35]
	v_cndmask_b32_e64 v206, v108, v100, s[34:35]
	v_cndmask_b32_e64 v245, v121, v109, s[34:35]
	v_cndmask_b32_e64 v207, v109, v101, s[34:35]
	v_cndmask_b32_e64 v246, v112, v104, s[34:35]
	v_cndmask_b32_e64 v208, v104, v96, s[34:35]
	v_cndmask_b32_e64 v247, v113, v105, s[34:35]
	v_cndmask_b32_e64 v209, v105, v97, s[34:35]
	v_fmac_f32_dpp v248, v244, v132 row_ror:15 row_mask:0xf bank_mask:0xf
	v_fmac_f32_dpp v212, v206, v132 row_ror:15 row_mask:0xf bank_mask:0xf
	v_fmac_f32_dpp v249, v245, v133 row_ror:15 row_mask:0xf bank_mask:0xf
	v_fmac_f32_dpp v213, v207, v133 row_ror:15 row_mask:0xf bank_mask:0xf
	v_fmac_f32_dpp v250, v246, v148 row_ror:15 row_mask:0xf bank_mask:0xf
	v_fmac_f32_dpp v214, v208, v148 row_ror:15 row_mask:0xf bank_mask:0xf
	v_fmac_f32_dpp v251, v247, v149 row_ror:15 row_mask:0xf bank_mask:0xf
	v_fmac_f32_dpp v215, v209, v149 row_ror:15 row_mask:0xf bank_mask:0xf
	v_pk_mul_f32 v[204:205], v[254:255], v[248:249]
	v_pk_mul_f32 v[220:221], v[254:255], v[212:213]
	v_exp_f32_e32 v204, v204
	v_exp_f32_e32 v220, v220
	v_exp_f32_e32 v205, v205
	v_exp_f32_e32 v221, v221
	v_pk_add_f32 v[204:205], v[204:205], v[252:253]
	v_pk_add_f32 v[220:221], v[220:221], v[252:253]
	v_rcp_f32_e32 v204, v204
	v_rcp_f32_e32 v220, v220
	v_rcp_f32_e32 v205, v205
	v_rcp_f32_e32 v221, v221
	v_pk_mul_f32 v[248:249], v[248:249], v[204:205]
	v_pk_mul_f32 v[212:213], v[212:213], v[220:221]
	v_pk_mul_f32 v[250:251], v[250:251], v[248:249]
	v_pk_mul_f32 v[214:215], v[214:215], v[212:213]
	s_nop 0
	s_nop 0
	s_nop 0
	s_nop 0
	s_nop 0
	v_cndmask_b32_e64 v222, v122, v162, vcc
	v_cndmask_b32_e64 v246, v110, v122, vcc
	v_cndmask_b32_e64 v223, v123, v163, vcc
	v_cndmask_b32_e64 v247, v111, v123, vcc
	v_cndmask_b32_e64 v242, v114, v158, vcc
	v_cndmask_b32_e64 v248, v106, v114, vcc
	v_cndmask_b32_e64 v243, v115, v159, vcc
	v_cndmask_b32_e64 v249, v107, v115, vcc
	v_pk_fma_f32 v[210:211], v[122:123], v[130:131], v[138:139]
	v_pk_fma_f32 v[204:205], v[110:111], v[130:131], v[138:139]
	v_pk_fma_f32 v[240:241], v[114:115], v[146:147], v[154:155]
	v_pk_fma_f32 v[206:207], v[106:107], v[146:147], v[154:155]
	v_fmac_f32_dpp v210, v222, v126 row_ror:1 row_mask:0xf bank_mask:0xf bound_ctrl:1
	v_fmac_f32_dpp v204, v246, v126 row_ror:1 row_mask:0xf bank_mask:0xf bound_ctrl:1
	v_fmac_f32_dpp v211, v223, v127 row_ror:1 row_mask:0xf bank_mask:0xf bound_ctrl:1
	v_fmac_f32_dpp v205, v247, v127 row_ror:1 row_mask:0xf bank_mask:0xf bound_ctrl:1
	v_fmac_f32_dpp v240, v242, v142 row_ror:1 row_mask:0xf bank_mask:0xf bound_ctrl:1
	v_fmac_f32_dpp v206, v248, v142 row_ror:1 row_mask:0xf bank_mask:0xf bound_ctrl:1
	v_fmac_f32_dpp v241, v243, v143 row_ror:1 row_mask:0xf bank_mask:0xf bound_ctrl:1
	v_fmac_f32_dpp v207, v249, v143 row_ror:1 row_mask:0xf bank_mask:0xf bound_ctrl:1
	v_cndmask_b32_e64 v222, v122, v110, s[34:35]
	v_cndmask_b32_e64 v246, v110, v102, s[34:35]
	v_cndmask_b32_e64 v223, v123, v111, s[34:35]
	v_cndmask_b32_e64 v247, v111, v103, s[34:35]
	v_cndmask_b32_e64 v242, v114, v106, s[34:35]
	v_cndmask_b32_e64 v248, v106, v98, s[34:35]
	v_cndmask_b32_e64 v243, v115, v107, s[34:35]
	v_cndmask_b32_e64 v249, v107, v99, s[34:35]
	v_fmac_f32_dpp v210, v222, v134 row_ror:15 row_mask:0xf bank_mask:0xf
	v_fmac_f32_dpp v204, v246, v134 row_ror:15 row_mask:0xf bank_mask:0xf
	v_fmac_f32_dpp v211, v223, v135 row_ror:15 row_mask:0xf bank_mask:0xf
	v_fmac_f32_dpp v205, v247, v135 row_ror:15 row_mask:0xf bank_mask:0xf
	v_fmac_f32_dpp v240, v242, v150 row_ror:15 row_mask:0xf bank_mask:0xf
	v_fmac_f32_dpp v206, v248, v150 row_ror:15 row_mask:0xf bank_mask:0xf
	v_fmac_f32_dpp v241, v243, v151 row_ror:15 row_mask:0xf bank_mask:0xf
	v_fmac_f32_dpp v207, v249, v151 row_ror:15 row_mask:0xf bank_mask:0xf
	v_pk_mul_f32 v[244:245], v[254:255], v[210:211]
	v_pk_mul_f32 v[208:209], v[254:255], v[204:205]
	v_exp_f32_e32 v244, v244
	v_exp_f32_e32 v208, v208
	v_exp_f32_e32 v245, v245
	v_exp_f32_e32 v209, v209
	v_pk_add_f32 v[244:245], v[244:245], v[252:253]
	v_pk_add_f32 v[208:209], v[208:209], v[252:253]
	v_rcp_f32_e32 v244, v244
	v_rcp_f32_e32 v208, v208
	v_rcp_f32_e32 v245, v245
	v_rcp_f32_e32 v209, v209
	v_pk_mul_f32 v[210:211], v[210:211], v[244:245]
	v_pk_mul_f32 v[204:205], v[204:205], v[208:209]
	v_pk_mul_f32 v[240:241], v[240:241], v[210:211]
	v_pk_mul_f32 v[206:207], v[206:207], v[204:205]
	s_nop 0
	s_nop 0
	s_nop 0
	s_nop 0
	v_cvt_pk_bf16_f32 v116, v250, v251
	v_cvt_pk_bf16_f32 v117, v240, v241
	s_nop 0
	s_nop 0
	s_nop 0
	s_nop 0
	s_nop 0
	s_nop 0
	v_cndmask_b32_e64 v212, v100, v108, vcc
	v_cndmask_b32_e64 v244, v102, v110, vcc
	v_cndmask_b32_e64 v213, v101, v109, vcc
	v_cndmask_b32_e64 v245, v103, v111, vcc
	v_cndmask_b32_e64 v220, v96, v104, vcc
	v_cndmask_b32_e64 v246, v98, v106, vcc
	v_cndmask_b32_e64 v221, v97, v105, vcc
	v_cndmask_b32_e64 v247, v99, v107, vcc
	v_pk_fma_f32 v[222:223], v[100:101], v[128:129], v[136:137]
	v_pk_fma_f32 v[248:249], v[102:103], v[130:131], v[138:139]
	v_pk_fma_f32 v[242:243], v[96:97], v[144:145], v[152:153]
	v_pk_fma_f32 v[204:205], v[98:99], v[146:147], v[154:155]
	v_fmac_f32_dpp v222, v212, v124 row_ror:1 row_mask:0xf bank_mask:0xf bound_ctrl:1
	v_fmac_f32_dpp v248, v244, v126 row_ror:1 row_mask:0xf bank_mask:0xf bound_ctrl:1
	v_fmac_f32_dpp v223, v213, v125 row_ror:1 row_mask:0xf bank_mask:0xf bound_ctrl:1
	v_fmac_f32_dpp v249, v245, v127 row_ror:1 row_mask:0xf bank_mask:0xf bound_ctrl:1
	v_fmac_f32_dpp v242, v220, v140 row_ror:1 row_mask:0xf bank_mask:0xf bound_ctrl:1
	v_fmac_f32_dpp v204, v246, v142 row_ror:1 row_mask:0xf bank_mask:0xf bound_ctrl:1
	v_fmac_f32_dpp v243, v221, v141 row_ror:1 row_mask:0xf bank_mask:0xf bound_ctrl:1
	v_fmac_f32_dpp v205, v247, v143 row_ror:1 row_mask:0xf bank_mask:0xf bound_ctrl:1
	v_cndmask_b32_e64 v212, v100, 0, s[34:35]
	v_cndmask_b32_e64 v244, v102, 0, s[34:35]
	v_cndmask_b32_e64 v213, v101, 0, s[34:35]
	v_cndmask_b32_e64 v245, v103, 0, s[34:35]
	v_cndmask_b32_e64 v220, v96, 0, s[34:35]
	v_cndmask_b32_e64 v246, v98, 0, s[34:35]
	v_cndmask_b32_e64 v221, v97, 0, s[34:35]
	v_cndmask_b32_e64 v247, v99, 0, s[34:35]
	v_fmac_f32_dpp v222, v212, v132 row_ror:15 row_mask:0xf bank_mask:0xf
	v_fmac_f32_dpp v248, v244, v134 row_ror:15 row_mask:0xf bank_mask:0xf
	v_fmac_f32_dpp v223, v213, v133 row_ror:15 row_mask:0xf bank_mask:0xf
	v_fmac_f32_dpp v249, v245, v135 row_ror:15 row_mask:0xf bank_mask:0xf
	v_fmac_f32_dpp v242, v220, v148 row_ror:15 row_mask:0xf bank_mask:0xf
	v_fmac_f32_dpp v204, v246, v150 row_ror:15 row_mask:0xf bank_mask:0xf
	v_fmac_f32_dpp v243, v221, v149 row_ror:15 row_mask:0xf bank_mask:0xf
	v_fmac_f32_dpp v205, v247, v151 row_ror:15 row_mask:0xf bank_mask:0xf
	v_pk_mul_f32 v[210:211], v[254:255], v[222:223]
	v_pk_mul_f32 v[208:209], v[254:255], v[248:249]
	v_exp_f32_e32 v210, v210
	v_exp_f32_e32 v208, v208
	v_exp_f32_e32 v211, v211
	v_exp_f32_e32 v209, v209
	v_pk_add_f32 v[210:211], v[210:211], v[252:253]
	v_pk_add_f32 v[208:209], v[208:209], v[252:253]
	v_rcp_f32_e32 v210, v210
	v_rcp_f32_e32 v208, v208
	v_rcp_f32_e32 v211, v211
	v_rcp_f32_e32 v209, v209
	v_pk_mul_f32 v[222:223], v[222:223], v[210:211]
	v_pk_mul_f32 v[248:249], v[248:249], v[208:209]
	v_pk_mul_f32 v[242:243], v[242:243], v[222:223]
	v_pk_mul_f32 v[204:205], v[204:205], v[248:249]
	v_cvt_pk_bf16_f32 v112, v214, v215
	v_cvt_pk_bf16_f32 v113, v206, v207
	s_nop 0
	s_nop 0
	s_nop 0
	s_nop 0
	s_nop 0
	s_nop 0
	s_nop 0
	s_nop 0
	v_cmp_lt_u32_e64 s[38:39], 13, v200
	v_add_u32_e32 v180, -12, v200
	v_cvt_pk_bf16_f32 v104, v242, v243
	v_cvt_pk_bf16_f32 v105, v204, v205
	s_and_saveexec_b64 s[10:11], s[38:39]
	s_cbranch_execz .LBB0_1409
	v_mov_b32_e32 v181, v165
	v_lshl_add_u64 v[106:107], s[52:53], 0, v[180:181]
	v_mov_b64_e32 v[108:109], s[0:1]
	s_movk_i32 s48, 0x2c00
	v_mad_u64_u32 v[108:109], s[40:41], v106, s48, v[108:109]
	v_mad_i32_i24 v109, v107, s48, v109
	v_lshl_add_u64 v[106:107], s[16:17], 1, v[108:109]
	s_lshl_b32 s48, s5, 1
	v_lshl_add_u64 v[106:107], v[106:107], 0, s[48:49]
	v_mov_b32_e32 v179, v165
	s_movk_i32 s66, 0x2c00
	v_lshl_add_u64 v[106:107], v[106:107], 0, v[178:179]
	v_cvt_pk_bf16_f32 v100, v100, v101
	v_cvt_pk_bf16_f32 v101, v102, v103
	global_store_dwordx2 v[106:107], v[100:101], off
	v_cvt_pk_bf16_f32 v96, v96, v97
	v_cvt_pk_bf16_f32 v97, v98, v99
	global_store_dwordx2 v[106:107], v[96:97], off offset:256
.LBB0_1409:
	s_or_b64 exec, exec, s[10:11]
	v_cndmask_b32_e64 v250, v92, 0, vcc
	v_cndmask_b32_e64 v210, v94, 0, vcc
	v_cndmask_b32_e64 v251, v93, 0, vcc
	v_cndmask_b32_e64 v211, v95, 0, vcc
	v_cndmask_b32_e64 v240, v88, 0, vcc
	v_cndmask_b32_e64 v244, v90, 0, vcc
	v_cndmask_b32_e64 v241, v89, 0, vcc
	v_cndmask_b32_e64 v245, v91, 0, vcc
	v_pk_fma_f32 v[212:213], v[92:93], v[128:129], v[136:137]
	v_pk_fma_f32 v[246:247], v[94:95], v[130:131], v[138:139]
	v_pk_fma_f32 v[220:221], v[88:89], v[144:145], v[152:153]
	v_pk_fma_f32 v[248:249], v[90:91], v[146:147], v[154:155]
	v_fmac_f32_dpp v212, v250, v124 row_ror:1 row_mask:0xf bank_mask:0xf bound_ctrl:1
	v_fmac_f32_dpp v246, v210, v126 row_ror:1 row_mask:0xf bank_mask:0xf bound_ctrl:1
	v_fmac_f32_dpp v213, v251, v125 row_ror:1 row_mask:0xf bank_mask:0xf bound_ctrl:1
	v_fmac_f32_dpp v247, v211, v127 row_ror:1 row_mask:0xf bank_mask:0xf bound_ctrl:1
	v_fmac_f32_dpp v220, v240, v140 row_ror:1 row_mask:0xf bank_mask:0xf bound_ctrl:1
	v_fmac_f32_dpp v248, v244, v142 row_ror:1 row_mask:0xf bank_mask:0xf bound_ctrl:1
	v_fmac_f32_dpp v221, v241, v141 row_ror:1 row_mask:0xf bank_mask:0xf bound_ctrl:1
	v_fmac_f32_dpp v249, v245, v143 row_ror:1 row_mask:0xf bank_mask:0xf bound_ctrl:1
	v_cndmask_b32_e64 v250, v92, v84, s[34:35]
	v_cndmask_b32_e64 v210, v94, v86, s[34:35]
	v_cndmask_b32_e64 v251, v93, v85, s[34:35]
	v_cndmask_b32_e64 v211, v95, v87, s[34:35]
	v_cndmask_b32_e64 v240, v88, v80, s[34:35]
	v_cndmask_b32_e64 v244, v90, v82, s[34:35]
	v_cndmask_b32_e64 v241, v89, v81, s[34:35]
	v_cndmask_b32_e64 v245, v91, v83, s[34:35]
	v_fmac_f32_dpp v212, v250, v132 row_ror:15 row_mask:0xf bank_mask:0xf
	v_fmac_f32_dpp v246, v210, v134 row_ror:15 row_mask:0xf bank_mask:0xf
	v_fmac_f32_dpp v213, v251, v133 row_ror:15 row_mask:0xf bank_mask:0xf
	v_fmac_f32_dpp v247, v211, v135 row_ror:15 row_mask:0xf bank_mask:0xf
	v_fmac_f32_dpp v220, v240, v148 row_ror:15 row_mask:0xf bank_mask:0xf
	v_fmac_f32_dpp v248, v244, v150 row_ror:15 row_mask:0xf bank_mask:0xf
	v_fmac_f32_dpp v221, v241, v149 row_ror:15 row_mask:0xf bank_mask:0xf
	v_fmac_f32_dpp v249, v245, v151 row_ror:15 row_mask:0xf bank_mask:0xf
	v_pk_mul_f32 v[222:223], v[254:255], v[212:213]
	v_pk_mul_f32 v[208:209], v[254:255], v[246:247]
	v_exp_f32_e32 v222, v222
	v_exp_f32_e32 v208, v208
	v_exp_f32_e32 v223, v223
	v_exp_f32_e32 v209, v209
	v_pk_add_f32 v[222:223], v[222:223], v[252:253]
	v_pk_add_f32 v[208:209], v[208:209], v[252:253]
	v_rcp_f32_e32 v222, v222
	v_rcp_f32_e32 v208, v208
	v_rcp_f32_e32 v223, v223
	v_rcp_f32_e32 v209, v209
	v_pk_mul_f32 v[212:213], v[212:213], v[222:223]
	v_pk_mul_f32 v[246:247], v[246:247], v[208:209]
	v_pk_mul_f32 v[220:221], v[220:221], v[212:213]
	v_pk_mul_f32 v[248:249], v[248:249], v[246:247]
	s_nop 0
	s_nop 0
	s_nop 0
	s_nop 0
	s_add_i32 s85, s31, 0x80
	s_ashr_i32 s10, s85, 6
	s_ashr_i32 s11, s10, 31
	s_lshl_b64 s[10:11], s[10:11], 2
	v_or_b32_e32 v156, s10, v200
	v_cvt_pk_bf16_f32 v96, v220, v221
	v_cvt_pk_bf16_f32 v97, v248, v249
	s_and_saveexec_b64 s[40:41], s[36:37]
	s_cbranch_execz .LBB0_1411
	v_mov_b64_e32 v[98:99], s[0:1]
	v_mad_i64_i32 v[98:99], s[86:87], v156, s66, v[98:99]
	v_lshl_add_u64 v[98:99], s[16:17], 1, v[98:99]
	s_lshl_b32 s48, s5, 1
	v_lshl_add_u64 v[98:99], v[98:99], 0, s[48:49]
	v_mov_b32_e32 v179, v165
	v_lshl_add_u64 v[98:99], v[98:99], 0, v[178:179]
	v_cvt_pk_bf16_f32 v100, v92, v93
	v_cvt_pk_bf16_f32 v101, v94, v95
	global_store_dwordx2 v[98:99], v[100:101], off
	v_cvt_pk_bf16_f32 v100, v88, v89
	v_cvt_pk_bf16_f32 v101, v90, v91
	global_store_dwordx2 v[98:99], v[100:101], off offset:256
.LBB0_1411:
	s_or_b64 exec, exec, s[40:41]
	v_cndmask_b32_e64 v214, v84, v92, vcc
	v_cndmask_b32_e64 v240, v86, v94, vcc
	v_cndmask_b32_e64 v215, v85, v93, vcc
	v_cndmask_b32_e64 v241, v87, v95, vcc
	v_cndmask_b32_e64 v206, v80, v88, vcc
	v_cndmask_b32_e64 v212, v82, v90, vcc
	v_cndmask_b32_e64 v207, v81, v89, vcc
	v_cndmask_b32_e64 v213, v83, v91, vcc
	v_pk_fma_f32 v[242:243], v[84:85], v[128:129], v[136:137]
	v_pk_fma_f32 v[222:223], v[86:87], v[130:131], v[138:139]
	v_pk_fma_f32 v[204:205], v[80:81], v[144:145], v[152:153]
	v_pk_fma_f32 v[210:211], v[82:83], v[146:147], v[154:155]
	v_fmac_f32_dpp v242, v214, v124 row_ror:1 row_mask:0xf bank_mask:0xf bound_ctrl:1
	v_fmac_f32_dpp v222, v240, v126 row_ror:1 row_mask:0xf bank_mask:0xf bound_ctrl:1
	v_fmac_f32_dpp v243, v215, v125 row_ror:1 row_mask:0xf bank_mask:0xf bound_ctrl:1
	v_fmac_f32_dpp v223, v241, v127 row_ror:1 row_mask:0xf bank_mask:0xf bound_ctrl:1
	v_fmac_f32_dpp v204, v206, v140 row_ror:1 row_mask:0xf bank_mask:0xf bound_ctrl:1
	v_fmac_f32_dpp v210, v212, v142 row_ror:1 row_mask:0xf bank_mask:0xf bound_ctrl:1
	v_fmac_f32_dpp v205, v207, v141 row_ror:1 row_mask:0xf bank_mask:0xf bound_ctrl:1
	v_fmac_f32_dpp v211, v213, v143 row_ror:1 row_mask:0xf bank_mask:0xf bound_ctrl:1
	v_cndmask_b32_e64 v214, v84, v76, s[34:35]
	v_cndmask_b32_e64 v240, v86, v78, s[34:35]
	v_cndmask_b32_e64 v215, v85, v77, s[34:35]
	v_cndmask_b32_e64 v241, v87, v79, s[34:35]
	v_cndmask_b32_e64 v206, v80, v72, s[34:35]
	v_cndmask_b32_e64 v212, v82, v74, s[34:35]
	v_cndmask_b32_e64 v207, v81, v73, s[34:35]
	v_cndmask_b32_e64 v213, v83, v75, s[34:35]
	v_fmac_f32_dpp v242, v214, v132 row_ror:15 row_mask:0xf bank_mask:0xf
	v_fmac_f32_dpp v222, v240, v134 row_ror:15 row_mask:0xf bank_mask:0xf
	v_fmac_f32_dpp v243, v215, v133 row_ror:15 row_mask:0xf bank_mask:0xf
	v_fmac_f32_dpp v223, v241, v135 row_ror:15 row_mask:0xf bank_mask:0xf
	v_fmac_f32_dpp v204, v206, v148 row_ror:15 row_mask:0xf bank_mask:0xf
	v_fmac_f32_dpp v210, v212, v150 row_ror:15 row_mask:0xf bank_mask:0xf
	v_fmac_f32_dpp v205, v207, v149 row_ror:15 row_mask:0xf bank_mask:0xf
	v_fmac_f32_dpp v211, v213, v151 row_ror:15 row_mask:0xf bank_mask:0xf
	v_pk_mul_f32 v[250:251], v[254:255], v[242:243]
	v_pk_mul_f32 v[244:245], v[254:255], v[222:223]
	v_exp_f32_e32 v250, v250
	v_exp_f32_e32 v244, v244
	v_exp_f32_e32 v251, v251
	v_exp_f32_e32 v245, v245
	v_pk_add_f32 v[250:251], v[250:251], v[252:253]
	v_pk_add_f32 v[244:245], v[244:245], v[252:253]
	v_rcp_f32_e32 v250, v250
	v_rcp_f32_e32 v244, v244
	v_rcp_f32_e32 v251, v251
	v_rcp_f32_e32 v245, v245
	v_pk_mul_f32 v[242:243], v[242:243], v[250:251]
	v_pk_mul_f32 v[222:223], v[222:223], v[244:245]
	v_pk_mul_f32 v[204:205], v[204:205], v[242:243]
	v_pk_mul_f32 v[210:211], v[210:211], v[222:223]
	s_nop 0
	s_nop 0
	s_nop 0
	s_nop 0
	s_nop 0
	s_nop 0
	s_nop 0
	s_nop 0
	s_nop 0
	v_cndmask_b32_e64 v246, v76, v84, vcc
	v_cndmask_b32_e64 v206, v78, v86, vcc
	v_cndmask_b32_e64 v247, v77, v85, vcc
	v_cndmask_b32_e64 v207, v79, v87, vcc
	v_cndmask_b32_e64 v208, v72, v80, vcc
	v_cndmask_b32_e64 v242, v74, v82, vcc
	v_cndmask_b32_e64 v209, v73, v81, vcc
	v_cndmask_b32_e64 v243, v75, v83, vcc
	v_pk_fma_f32 v[220:221], v[76:77], v[128:129], v[136:137]
	v_pk_fma_f32 v[250:251], v[78:79], v[130:131], v[138:139]
	v_pk_fma_f32 v[248:249], v[72:73], v[144:145], v[152:153]
	v_pk_fma_f32 v[240:241], v[74:75], v[146:147], v[154:155]
	v_fmac_f32_dpp v220, v246, v124 row_ror:1 row_mask:0xf bank_mask:0xf bound_ctrl:1
	v_fmac_f32_dpp v250, v206, v126 row_ror:1 row_mask:0xf bank_mask:0xf bound_ctrl:1
	v_fmac_f32_dpp v221, v247, v125 row_ror:1 row_mask:0xf bank_mask:0xf bound_ctrl:1
	v_fmac_f32_dpp v251, v207, v127 row_ror:1 row_mask:0xf bank_mask:0xf bound_ctrl:1
	v_fmac_f32_dpp v248, v208, v140 row_ror:1 row_mask:0xf bank_mask:0xf bound_ctrl:1
	v_fmac_f32_dpp v240, v242, v142 row_ror:1 row_mask:0xf bank_mask:0xf bound_ctrl:1
	v_fmac_f32_dpp v249, v209, v141 row_ror:1 row_mask:0xf bank_mask:0xf bound_ctrl:1
	v_fmac_f32_dpp v241, v243, v143 row_ror:1 row_mask:0xf bank_mask:0xf bound_ctrl:1
	v_cndmask_b32_e64 v246, v76, v68, s[34:35]
	v_cndmask_b32_e64 v206, v78, v70, s[34:35]
	v_cndmask_b32_e64 v247, v77, v69, s[34:35]
	v_cndmask_b32_e64 v207, v79, v71, s[34:35]
	v_cndmask_b32_e64 v208, v72, v64, s[34:35]
	v_cndmask_b32_e64 v242, v74, v66, s[34:35]
	v_cndmask_b32_e64 v209, v73, v65, s[34:35]
	v_cndmask_b32_e64 v243, v75, v67, s[34:35]
	v_fmac_f32_dpp v220, v246, v132 row_ror:15 row_mask:0xf bank_mask:0xf
	v_fmac_f32_dpp v250, v206, v134 row_ror:15 row_mask:0xf bank_mask:0xf
	v_fmac_f32_dpp v221, v247, v133 row_ror:15 row_mask:0xf bank_mask:0xf
	v_fmac_f32_dpp v251, v207, v135 row_ror:15 row_mask:0xf bank_mask:0xf
	v_fmac_f32_dpp v248, v208, v148 row_ror:15 row_mask:0xf bank_mask:0xf
	v_fmac_f32_dpp v240, v242, v150 row_ror:15 row_mask:0xf bank_mask:0xf
	v_fmac_f32_dpp v249, v209, v149 row_ror:15 row_mask:0xf bank_mask:0xf
	v_fmac_f32_dpp v241, v243, v151 row_ror:15 row_mask:0xf bank_mask:0xf
	v_pk_mul_f32 v[214:215], v[254:255], v[220:221]
	v_pk_mul_f32 v[212:213], v[254:255], v[250:251]
	v_exp_f32_e32 v214, v214
	v_exp_f32_e32 v212, v212
	v_exp_f32_e32 v215, v215
	v_exp_f32_e32 v213, v213
	v_pk_add_f32 v[214:215], v[214:215], v[252:253]
	v_pk_add_f32 v[212:213], v[212:213], v[252:253]
	v_rcp_f32_e32 v214, v214
	v_rcp_f32_e32 v212, v212
	v_rcp_f32_e32 v215, v215
	v_rcp_f32_e32 v213, v213
	v_pk_mul_f32 v[220:221], v[220:221], v[214:215]
	v_pk_mul_f32 v[250:251], v[250:251], v[212:213]
	v_pk_mul_f32 v[248:249], v[248:249], v[220:221]
	v_pk_mul_f32 v[240:241], v[240:241], v[250:251]
	v_cvt_pk_bf16_f32 v88, v204, v205
	v_cvt_pk_bf16_f32 v89, v210, v211
	s_nop 0
	s_nop 0
	s_nop 0
	s_nop 0
	s_nop 0
	s_nop 0
	s_nop 0
	s_nop 0
	v_cndmask_b32_e64 v222, v68, v76, vcc
	v_cndmask_b32_e64 v214, v70, v78, vcc
	v_cndmask_b32_e64 v223, v69, v77, vcc
	v_cndmask_b32_e64 v215, v71, v79, vcc
	v_cndmask_b32_e64 v244, v64, v72, vcc
	v_cndmask_b32_e64 v206, v66, v74, vcc
	v_cndmask_b32_e64 v245, v65, v73, vcc
	v_cndmask_b32_e64 v207, v67, v75, vcc
	v_pk_fma_f32 v[246:247], v[68:69], v[128:129], v[136:137]
	v_pk_fma_f32 v[242:243], v[70:71], v[130:131], v[138:139]
	v_pk_fma_f32 v[208:209], v[64:65], v[144:145], v[152:153]
	v_pk_fma_f32 v[250:251], v[66:67], v[146:147], v[154:155]
	v_fmac_f32_dpp v246, v222, v124 row_ror:1 row_mask:0xf bank_mask:0xf bound_ctrl:1
	v_fmac_f32_dpp v242, v214, v126 row_ror:1 row_mask:0xf bank_mask:0xf bound_ctrl:1
	v_fmac_f32_dpp v247, v223, v125 row_ror:1 row_mask:0xf bank_mask:0xf bound_ctrl:1
	v_fmac_f32_dpp v243, v215, v127 row_ror:1 row_mask:0xf bank_mask:0xf bound_ctrl:1
	v_fmac_f32_dpp v208, v244, v140 row_ror:1 row_mask:0xf bank_mask:0xf bound_ctrl:1
	v_fmac_f32_dpp v250, v206, v142 row_ror:1 row_mask:0xf bank_mask:0xf bound_ctrl:1
	v_fmac_f32_dpp v209, v245, v141 row_ror:1 row_mask:0xf bank_mask:0xf bound_ctrl:1
	v_fmac_f32_dpp v251, v207, v143 row_ror:1 row_mask:0xf bank_mask:0xf bound_ctrl:1
	v_cndmask_b32_e64 v222, v68, 0, s[34:35]
	v_cndmask_b32_e64 v214, v70, 0, s[34:35]
	v_cndmask_b32_e64 v223, v69, 0, s[34:35]
	v_cndmask_b32_e64 v215, v71, 0, s[34:35]
	v_cndmask_b32_e64 v244, v64, 0, s[34:35]
	v_cndmask_b32_e64 v206, v66, 0, s[34:35]
	v_cndmask_b32_e64 v245, v65, 0, s[34:35]
	v_cndmask_b32_e64 v207, v67, 0, s[34:35]
	v_fmac_f32_dpp v246, v222, v132 row_ror:15 row_mask:0xf bank_mask:0xf
	v_fmac_f32_dpp v242, v214, v134 row_ror:15 row_mask:0xf bank_mask:0xf
	v_fmac_f32_dpp v247, v223, v133 row_ror:15 row_mask:0xf bank_mask:0xf
	v_fmac_f32_dpp v243, v215, v135 row_ror:15 row_mask:0xf bank_mask:0xf
	v_fmac_f32_dpp v208, v244, v148 row_ror:15 row_mask:0xf bank_mask:0xf
	v_fmac_f32_dpp v250, v206, v150 row_ror:15 row_mask:0xf bank_mask:0xf
	v_fmac_f32_dpp v209, v245, v149 row_ror:15 row_mask:0xf bank_mask:0xf
	v_fmac_f32_dpp v251, v207, v151 row_ror:15 row_mask:0xf bank_mask:0xf
	v_pk_mul_f32 v[220:221], v[254:255], v[246:247]
	v_pk_mul_f32 v[212:213], v[254:255], v[242:243]
	v_exp_f32_e32 v220, v220
	v_exp_f32_e32 v212, v212
	v_exp_f32_e32 v221, v221
	v_exp_f32_e32 v213, v213
	v_pk_add_f32 v[220:221], v[220:221], v[252:253]
	v_pk_add_f32 v[212:213], v[212:213], v[252:253]
	v_rcp_f32_e32 v220, v220
	v_rcp_f32_e32 v212, v212
	v_rcp_f32_e32 v221, v221
	v_rcp_f32_e32 v213, v213
	v_pk_mul_f32 v[246:247], v[246:247], v[220:221]
	v_pk_mul_f32 v[242:243], v[242:243], v[212:213]
	v_pk_mul_f32 v[208:209], v[208:209], v[246:247]
	v_pk_mul_f32 v[250:251], v[250:251], v[242:243]
	v_cvt_pk_bf16_f32 v80, v248, v249
	v_cvt_pk_bf16_f32 v81, v240, v241
	s_nop 0
	s_nop 0
	s_nop 0
	s_nop 0
	s_nop 0
	s_nop 0
	s_nop 0
	s_nop 0
	v_cvt_pk_bf16_f32 v72, v208, v209
	v_cvt_pk_bf16_f32 v73, v250, v251
	s_and_saveexec_b64 s[40:41], s[38:39]
	s_cbranch_execz .LBB0_1413
	v_mov_b32_e32 v181, v165
	v_lshl_add_u64 v[74:75], s[10:11], 0, v[180:181]
	v_mov_b64_e32 v[76:77], s[0:1]
	s_movk_i32 s48, 0x2c00
	v_mad_u64_u32 v[76:77], s[86:87], v74, s48, v[76:77]
	v_mad_i32_i24 v77, v75, s48, v77
	v_lshl_add_u64 v[74:75], s[16:17], 1, v[76:77]
	s_lshl_b32 s48, s5, 1
	v_lshl_add_u64 v[74:75], v[74:75], 0, s[48:49]
	v_mov_b32_e32 v179, v165
	s_movk_i32 s66, 0x2c00
	v_lshl_add_u64 v[74:75], v[74:75], 0, v[178:179]
	v_cvt_pk_bf16_f32 v68, v68, v69
	v_cvt_pk_bf16_f32 v69, v70, v71
	global_store_dwordx2 v[74:75], v[68:69], off
	v_cvt_pk_bf16_f32 v64, v64, v65
	v_cvt_pk_bf16_f32 v65, v66, v67
	global_store_dwordx2 v[74:75], v[64:65], off offset:256
.LBB0_1413:
	s_or_b64 exec, exec, s[40:41]
	v_or_b32_e32 v68, 4, v182
	v_ashrrev_i32_e32 v69, 31, v68
	v_lshlrev_b64 v[82:83], 2, v[68:69]
	global_load_dwordx4 v[64:67], v[184:185], off offset:16
	v_lshl_add_u64 v[68:69], s[58:59], 0, v[82:83]
	global_load_dwordx4 v[68:71], v[68:69], off
	v_lshl_add_u64 v[74:75], s[60:61], 0, v[82:83]
	global_load_dwordx4 v[74:77], v[74:75], off
	s_nop 0
	global_load_dwordx4 v[84:87], v[186:187], off offset:16
	v_lshl_add_u64 v[90:91], s[12:13], 0, v[82:83]
	global_load_dwordx4 v[92:95], v[90:91], off
	v_lshl_add_u64 v[90:91], s[50:51], 0, v[82:83]
	global_load_dwordx4 v[100:103], v[90:91], off
	v_lshl_add_u64 v[90:91], s[20:21], 0, v[82:83]
	global_load_dwordx4 v[108:111], v[90:91], off
	v_lshl_add_u64 v[82:83], s[44:45], 0, v[82:83]
	global_load_dwordx4 v[122:125], v[82:83], off
	s_nop 0
	v_mov_b32_e32 v106, v165
	s_ashr_i32 s40, s6, 6
	s_ashr_i32 s41, s40, 31
	s_ashr_i32 s31, s31, 8
	s_lshl_b64 s[40:41], s[40:41], 15
	v_or_b32_e32 v78, s7, v200
	v_mov_b32_e32 v107, v165
	s_add_u32 s86, s80, s40
	s_mul_hi_i32 s7, s31, 0x160000
	s_mul_i32 s31, s31, 0x160000
	v_and_b32_e32 v82, 56, v182
	v_lshlrev_b32_e32 v78, 6, v78
	s_movk_i32 s6, 0x33c0
	s_addc_u32 s87, s81, s41
	v_and_or_b32 v78, v78, s6, v82
	s_add_u32 s40, s86, s31
	s_addc_u32 s41, s87, s7
	v_lshlrev_b32_e32 v164, 1, v78
	s_waitcnt vmcnt(0)
	v_cndmask_b32_e64 v204, v60, 0, vcc
	v_cndmask_b32_e64 v220, v62, 0, vcc
	v_cndmask_b32_e64 v205, v61, 0, vcc
	v_cndmask_b32_e64 v221, v63, 0, vcc
	v_cndmask_b32_e64 v210, v56, 0, vcc
	v_cndmask_b32_e64 v214, v58, 0, vcc
	v_cndmask_b32_e64 v211, v57, 0, vcc
	v_cndmask_b32_e64 v215, v59, 0, vcc
	v_pk_fma_f32 v[222:223], v[60:61], v[68:69], v[84:85]
	v_pk_fma_f32 v[206:207], v[62:63], v[70:71], v[86:87]
	v_pk_fma_f32 v[244:245], v[56:57], v[100:101], v[122:123]
	v_pk_fma_f32 v[242:243], v[58:59], v[102:103], v[124:125]
	v_fmac_f32_dpp v222, v204, v64 row_ror:1 row_mask:0xf bank_mask:0xf bound_ctrl:1
	v_fmac_f32_dpp v206, v220, v66 row_ror:1 row_mask:0xf bank_mask:0xf bound_ctrl:1
	v_fmac_f32_dpp v223, v205, v65 row_ror:1 row_mask:0xf bank_mask:0xf bound_ctrl:1
	v_fmac_f32_dpp v207, v221, v67 row_ror:1 row_mask:0xf bank_mask:0xf bound_ctrl:1
	v_fmac_f32_dpp v244, v210, v92 row_ror:1 row_mask:0xf bank_mask:0xf bound_ctrl:1
	v_fmac_f32_dpp v242, v214, v94 row_ror:1 row_mask:0xf bank_mask:0xf bound_ctrl:1
	v_fmac_f32_dpp v245, v211, v93 row_ror:1 row_mask:0xf bank_mask:0xf bound_ctrl:1
	v_fmac_f32_dpp v243, v215, v95 row_ror:1 row_mask:0xf bank_mask:0xf bound_ctrl:1
	v_cndmask_b32_e64 v204, v60, v52, s[34:35]
	v_cndmask_b32_e64 v220, v62, v54, s[34:35]
	v_cndmask_b32_e64 v205, v61, v53, s[34:35]
	v_cndmask_b32_e64 v221, v63, v55, s[34:35]
	v_cndmask_b32_e64 v210, v56, v48, s[34:35]
	v_cndmask_b32_e64 v214, v58, v50, s[34:35]
	v_cndmask_b32_e64 v211, v57, v49, s[34:35]
	v_cndmask_b32_e64 v215, v59, v51, s[34:35]
	v_fmac_f32_dpp v222, v204, v74 row_ror:15 row_mask:0xf bank_mask:0xf
	v_fmac_f32_dpp v206, v220, v76 row_ror:15 row_mask:0xf bank_mask:0xf
	v_fmac_f32_dpp v223, v205, v75 row_ror:15 row_mask:0xf bank_mask:0xf
	v_fmac_f32_dpp v207, v221, v77 row_ror:15 row_mask:0xf bank_mask:0xf
	v_fmac_f32_dpp v244, v210, v108 row_ror:15 row_mask:0xf bank_mask:0xf
	v_fmac_f32_dpp v242, v214, v110 row_ror:15 row_mask:0xf bank_mask:0xf
	v_fmac_f32_dpp v245, v211, v109 row_ror:15 row_mask:0xf bank_mask:0xf
	v_fmac_f32_dpp v243, v215, v111 row_ror:15 row_mask:0xf bank_mask:0xf
	v_pk_mul_f32 v[246:247], v[254:255], v[222:223]
	v_pk_mul_f32 v[212:213], v[254:255], v[206:207]
	v_exp_f32_e32 v246, v246
	v_exp_f32_e32 v212, v212
	v_exp_f32_e32 v247, v247
	v_exp_f32_e32 v213, v213
	v_pk_add_f32 v[246:247], v[246:247], v[252:253]
	v_pk_add_f32 v[212:213], v[212:213], v[252:253]
	v_rcp_f32_e32 v246, v246
	v_rcp_f32_e32 v212, v212
	v_rcp_f32_e32 v247, v247
	v_rcp_f32_e32 v213, v213
	v_pk_mul_f32 v[222:223], v[222:223], v[246:247]
	v_pk_mul_f32 v[206:207], v[206:207], v[212:213]
	v_pk_mul_f32 v[244:245], v[244:245], v[222:223]
	v_pk_mul_f32 v[242:243], v[242:243], v[206:207]
	s_nop 1
	s_nop 0
	v_cvt_pk_bf16_f32 v120, v244, v245
	v_cvt_pk_bf16_f32 v121, v242, v243
	global_store_dwordx4 v164, v[118:121], s[40:41]
	s_and_saveexec_b64 s[6:7], s[36:37]
	s_cbranch_execz .LBB0_1415
	v_mov_b64_e32 v[78:79], s[0:1]
	v_mad_i64_i32 v[78:79], s[88:89], v183, s66, v[78:79]
	v_lshl_add_u64 v[78:79], s[16:17], 1, v[78:79]
	s_lshl_b32 s48, s5, 1
	v_lshl_add_u64 v[78:79], v[78:79], 0, s[48:49]
	v_mov_b32_e32 v179, v165
	v_lshl_add_u64 v[78:79], v[78:79], 0, v[178:179]
	v_cvt_pk_bf16_f32 v90, v60, v61
	v_cvt_pk_bf16_f32 v91, v62, v63
	global_store_dwordx2 v[78:79], v[90:91], off offset:8
	v_cvt_pk_bf16_f32 v90, v56, v57
	v_cvt_pk_bf16_f32 v91, v58, v59
	global_store_dwordx2 v[78:79], v[90:91], off offset:264
.LBB0_1415:
	s_or_b64 exec, exec, s[6:7]
	v_cndmask_b32_e64 v248, v52, v60, vcc
	v_cndmask_b32_e64 v210, v54, v62, vcc
	v_cndmask_b32_e64 v249, v53, v61, vcc
	v_cndmask_b32_e64 v211, v55, v63, vcc
	v_cndmask_b32_e64 v240, v48, v56, vcc
	v_cndmask_b32_e64 v222, v50, v58, vcc
	v_cndmask_b32_e64 v241, v49, v57, vcc
	v_cndmask_b32_e64 v223, v51, v59, vcc
	v_pk_fma_f32 v[208:209], v[52:53], v[68:69], v[84:85]
	v_pk_fma_f32 v[246:247], v[54:55], v[70:71], v[86:87]
	v_pk_fma_f32 v[250:251], v[48:49], v[100:101], v[122:123]
	v_pk_fma_f32 v[220:221], v[50:51], v[102:103], v[124:125]
	v_fmac_f32_dpp v208, v248, v64 row_ror:1 row_mask:0xf bank_mask:0xf bound_ctrl:1
	v_fmac_f32_dpp v246, v210, v66 row_ror:1 row_mask:0xf bank_mask:0xf bound_ctrl:1
	v_fmac_f32_dpp v209, v249, v65 row_ror:1 row_mask:0xf bank_mask:0xf bound_ctrl:1
	v_fmac_f32_dpp v247, v211, v67 row_ror:1 row_mask:0xf bank_mask:0xf bound_ctrl:1
	v_fmac_f32_dpp v250, v240, v92 row_ror:1 row_mask:0xf bank_mask:0xf bound_ctrl:1
	v_fmac_f32_dpp v220, v222, v94 row_ror:1 row_mask:0xf bank_mask:0xf bound_ctrl:1
	v_fmac_f32_dpp v251, v241, v93 row_ror:1 row_mask:0xf bank_mask:0xf bound_ctrl:1
	v_fmac_f32_dpp v221, v223, v95 row_ror:1 row_mask:0xf bank_mask:0xf bound_ctrl:1
	v_cndmask_b32_e64 v248, v52, v44, s[34:35]
	v_cndmask_b32_e64 v210, v54, v46, s[34:35]
	v_cndmask_b32_e64 v249, v53, v45, s[34:35]
	v_cndmask_b32_e64 v211, v55, v47, s[34:35]
	v_cndmask_b32_e64 v240, v48, v40, s[34:35]
	v_cndmask_b32_e64 v222, v50, v42, s[34:35]
	v_cndmask_b32_e64 v241, v49, v41, s[34:35]
	v_cndmask_b32_e64 v223, v51, v43, s[34:35]
	v_fmac_f32_dpp v208, v248, v74 row_ror:15 row_mask:0xf bank_mask:0xf
	v_fmac_f32_dpp v246, v210, v76 row_ror:15 row_mask:0xf bank_mask:0xf
	v_fmac_f32_dpp v209, v249, v75 row_ror:15 row_mask:0xf bank_mask:0xf
	v_fmac_f32_dpp v247, v211, v77 row_ror:15 row_mask:0xf bank_mask:0xf
	v_fmac_f32_dpp v250, v240, v108 row_ror:15 row_mask:0xf bank_mask:0xf
	v_fmac_f32_dpp v220, v222, v110 row_ror:15 row_mask:0xf bank_mask:0xf
	v_fmac_f32_dpp v251, v241, v109 row_ror:15 row_mask:0xf bank_mask:0xf
	v_fmac_f32_dpp v221, v223, v111 row_ror:15 row_mask:0xf bank_mask:0xf
	v_pk_mul_f32 v[204:205], v[254:255], v[208:209]
	v_pk_mul_f32 v[214:215], v[254:255], v[246:247]
	v_exp_f32_e32 v204, v204
	v_exp_f32_e32 v214, v214
	v_exp_f32_e32 v205, v205
	v_exp_f32_e32 v215, v215
	v_pk_add_f32 v[204:205], v[204:205], v[252:253]
	v_pk_add_f32 v[214:215], v[214:215], v[252:253]
	v_rcp_f32_e32 v204, v204
	v_rcp_f32_e32 v214, v214
	v_rcp_f32_e32 v205, v205
	v_rcp_f32_e32 v215, v215
	v_pk_mul_f32 v[208:209], v[208:209], v[204:205]
	v_pk_mul_f32 v[246:247], v[246:247], v[214:215]
	v_pk_mul_f32 v[250:251], v[250:251], v[208:209]
	v_pk_mul_f32 v[220:221], v[220:221], v[246:247]
	s_nop 0
	s_nop 0
	s_nop 0
	s_nop 0
	s_nop 0
	s_nop 0
	v_cndmask_b32_e64 v206, v44, v52, vcc
	v_cndmask_b32_e64 v240, v46, v54, vcc
	v_cndmask_b32_e64 v207, v45, v53, vcc
	v_cndmask_b32_e64 v241, v47, v55, vcc
	v_cndmask_b32_e64 v212, v40, v48, vcc
	v_cndmask_b32_e64 v208, v42, v50, vcc
	v_cndmask_b32_e64 v213, v41, v49, vcc
	v_cndmask_b32_e64 v209, v43, v51, vcc
	v_pk_fma_f32 v[244:245], v[44:45], v[68:69], v[84:85]
	v_pk_fma_f32 v[204:205], v[46:47], v[70:71], v[86:87]
	v_pk_fma_f32 v[242:243], v[40:41], v[100:101], v[122:123]
	v_pk_fma_f32 v[210:211], v[42:43], v[102:103], v[124:125]
	v_fmac_f32_dpp v244, v206, v64 row_ror:1 row_mask:0xf bank_mask:0xf bound_ctrl:1
	v_fmac_f32_dpp v204, v240, v66 row_ror:1 row_mask:0xf bank_mask:0xf bound_ctrl:1
	v_fmac_f32_dpp v245, v207, v65 row_ror:1 row_mask:0xf bank_mask:0xf bound_ctrl:1
	v_fmac_f32_dpp v205, v241, v67 row_ror:1 row_mask:0xf bank_mask:0xf bound_ctrl:1
	v_fmac_f32_dpp v242, v212, v92 row_ror:1 row_mask:0xf bank_mask:0xf bound_ctrl:1
	v_fmac_f32_dpp v210, v208, v94 row_ror:1 row_mask:0xf bank_mask:0xf bound_ctrl:1
	v_fmac_f32_dpp v243, v213, v93 row_ror:1 row_mask:0xf bank_mask:0xf bound_ctrl:1
	v_fmac_f32_dpp v211, v209, v95 row_ror:1 row_mask:0xf bank_mask:0xf bound_ctrl:1
	v_cndmask_b32_e64 v206, v44, v36, s[34:35]
	v_cndmask_b32_e64 v240, v46, v38, s[34:35]
	v_cndmask_b32_e64 v207, v45, v37, s[34:35]
	v_cndmask_b32_e64 v241, v47, v39, s[34:35]
	v_cndmask_b32_e64 v212, v40, v32, s[34:35]
	v_cndmask_b32_e64 v208, v42, v34, s[34:35]
	v_cndmask_b32_e64 v213, v41, v33, s[34:35]
	v_cndmask_b32_e64 v209, v43, v35, s[34:35]
	v_fmac_f32_dpp v244, v206, v74 row_ror:15 row_mask:0xf bank_mask:0xf
	v_fmac_f32_dpp v204, v240, v76 row_ror:15 row_mask:0xf bank_mask:0xf
	v_fmac_f32_dpp v245, v207, v75 row_ror:15 row_mask:0xf bank_mask:0xf
	v_fmac_f32_dpp v205, v241, v77 row_ror:15 row_mask:0xf bank_mask:0xf
	v_fmac_f32_dpp v242, v212, v108 row_ror:15 row_mask:0xf bank_mask:0xf
	v_fmac_f32_dpp v210, v208, v110 row_ror:15 row_mask:0xf bank_mask:0xf
	v_fmac_f32_dpp v243, v213, v109 row_ror:15 row_mask:0xf bank_mask:0xf
	v_fmac_f32_dpp v211, v209, v111 row_ror:15 row_mask:0xf bank_mask:0xf
	v_pk_mul_f32 v[248:249], v[254:255], v[244:245]
	v_pk_mul_f32 v[222:223], v[254:255], v[204:205]
	v_exp_f32_e32 v248, v248
	v_exp_f32_e32 v222, v222
	v_exp_f32_e32 v249, v249
	v_exp_f32_e32 v223, v223
	v_pk_add_f32 v[248:249], v[248:249], v[252:253]
	v_pk_add_f32 v[222:223], v[222:223], v[252:253]
	v_rcp_f32_e32 v248, v248
	v_rcp_f32_e32 v222, v222
	v_rcp_f32_e32 v249, v249
	v_rcp_f32_e32 v223, v223
	v_pk_mul_f32 v[244:245], v[244:245], v[248:249]
	v_pk_mul_f32 v[204:205], v[204:205], v[222:223]
	v_pk_mul_f32 v[242:243], v[242:243], v[244:245]
	v_pk_mul_f32 v[210:211], v[210:211], v[204:205]
	s_nop 0
	s_nop 0
	s_nop 0
	v_cvt_pk_bf16_f32 v118, v250, v251
	s_nop 0
	s_nop 0
	v_cvt_pk_bf16_f32 v119, v220, v221
	s_nop 0
	s_nop 0
	s_nop 0
	v_cndmask_b32_e64 v246, v36, v44, vcc
	v_cndmask_b32_e64 v248, v38, v46, vcc
	v_cndmask_b32_e64 v247, v37, v45, vcc
	v_cndmask_b32_e64 v249, v39, v47, vcc
	v_cndmask_b32_e64 v214, v32, v40, vcc
	v_cndmask_b32_e64 v240, v34, v42, vcc
	v_cndmask_b32_e64 v215, v33, v41, vcc
	v_cndmask_b32_e64 v241, v35, v43, vcc
	v_pk_fma_f32 v[206:207], v[36:37], v[68:69], v[84:85]
	v_pk_fma_f32 v[208:209], v[38:39], v[70:71], v[86:87]
	v_pk_fma_f32 v[212:213], v[32:33], v[100:101], v[122:123]
	v_pk_fma_f32 v[204:205], v[34:35], v[102:103], v[124:125]
	v_fmac_f32_dpp v206, v246, v64 row_ror:1 row_mask:0xf bank_mask:0xf bound_ctrl:1
	v_fmac_f32_dpp v208, v248, v66 row_ror:1 row_mask:0xf bank_mask:0xf bound_ctrl:1
	v_fmac_f32_dpp v207, v247, v65 row_ror:1 row_mask:0xf bank_mask:0xf bound_ctrl:1
	v_fmac_f32_dpp v209, v249, v67 row_ror:1 row_mask:0xf bank_mask:0xf bound_ctrl:1
	v_fmac_f32_dpp v212, v214, v92 row_ror:1 row_mask:0xf bank_mask:0xf bound_ctrl:1
	v_fmac_f32_dpp v204, v240, v94 row_ror:1 row_mask:0xf bank_mask:0xf bound_ctrl:1
	v_fmac_f32_dpp v213, v215, v93 row_ror:1 row_mask:0xf bank_mask:0xf bound_ctrl:1
	v_fmac_f32_dpp v205, v241, v95 row_ror:1 row_mask:0xf bank_mask:0xf bound_ctrl:1
	v_cndmask_b32_e64 v246, v36, 0, s[34:35]
	v_cndmask_b32_e64 v248, v38, 0, s[34:35]
	v_cndmask_b32_e64 v247, v37, 0, s[34:35]
	v_cndmask_b32_e64 v249, v39, 0, s[34:35]
	v_cndmask_b32_e64 v214, v32, 0, s[34:35]
	v_cndmask_b32_e64 v240, v34, 0, s[34:35]
	v_cndmask_b32_e64 v215, v33, 0, s[34:35]
	v_cndmask_b32_e64 v241, v35, 0, s[34:35]
	v_fmac_f32_dpp v206, v246, v74 row_ror:15 row_mask:0xf bank_mask:0xf
	v_fmac_f32_dpp v208, v248, v76 row_ror:15 row_mask:0xf bank_mask:0xf
	v_fmac_f32_dpp v207, v247, v75 row_ror:15 row_mask:0xf bank_mask:0xf
	v_fmac_f32_dpp v209, v249, v77 row_ror:15 row_mask:0xf bank_mask:0xf
	v_fmac_f32_dpp v212, v214, v108 row_ror:15 row_mask:0xf bank_mask:0xf
	v_fmac_f32_dpp v204, v240, v110 row_ror:15 row_mask:0xf bank_mask:0xf
	v_fmac_f32_dpp v213, v215, v109 row_ror:15 row_mask:0xf bank_mask:0xf
	v_fmac_f32_dpp v205, v241, v111 row_ror:15 row_mask:0xf bank_mask:0xf
	v_pk_mul_f32 v[244:245], v[254:255], v[206:207]
	v_pk_mul_f32 v[222:223], v[254:255], v[208:209]
	v_exp_f32_e32 v244, v244
	v_exp_f32_e32 v222, v222
	v_exp_f32_e32 v245, v245
	v_exp_f32_e32 v223, v223
	v_pk_add_f32 v[244:245], v[244:245], v[252:253]
	v_pk_add_f32 v[222:223], v[222:223], v[252:253]
	v_rcp_f32_e32 v244, v244
	v_rcp_f32_e32 v222, v222
	v_rcp_f32_e32 v245, v245
	v_rcp_f32_e32 v223, v223
	v_pk_mul_f32 v[206:207], v[206:207], v[244:245]
	v_pk_mul_f32 v[208:209], v[208:209], v[222:223]
	v_pk_mul_f32 v[212:213], v[212:213], v[206:207]
	v_pk_mul_f32 v[204:205], v[204:205], v[208:209]
	v_cvt_pk_bf16_f32 v115, v210, v211
	s_nop 0
	s_nop 0
	s_nop 0
	v_lshl_add_u64 v[78:79], s[40:41], 0, v[164:165]
	s_movk_i32 s6, 0x1000
	v_cvt_pk_bf16_f32 v114, v242, v243
	v_add_co_u32_e64 v48, s[40:41], s6, v78
	s_nop 0
	s_nop 0
	v_addc_co_u32_e64 v49, s[40:41], 0, v79, s[40:41]
	global_store_dwordx4 v[78:79], v[116:119], off offset:2048
	global_store_dwordx4 v[48:49], v[112:115], off
	v_cvt_pk_bf16_f32 v106, v212, v213
	v_cvt_pk_bf16_f32 v107, v204, v205
	global_store_dwordx4 v[48:49], v[104:107], off offset:2048
	s_and_saveexec_b64 s[40:41], s[38:39]
	s_cbranch_execz .LBB0_1417
	v_mov_b32_e32 v181, v165
	v_lshl_add_u64 v[40:41], s[52:53], 0, v[180:181]
	v_mov_b64_e32 v[42:43], s[0:1]
	s_movk_i32 s31, 0x2c00
	v_mad_u64_u32 v[42:43], s[6:7], v40, s31, v[42:43]
	v_mad_i32_i24 v43, v41, s31, v43
	v_lshl_add_u64 v[40:41], s[16:17], 1, v[42:43]
	s_lshl_b32 s48, s5, 1
	v_lshl_add_u64 v[40:41], v[40:41], 0, s[48:49]
	v_mov_b32_e32 v179, v165
	s_movk_i32 s66, 0x2c00
	v_lshl_add_u64 v[40:41], v[40:41], 0, v[178:179]
	v_cvt_pk_bf16_f32 v36, v36, v37
	v_cvt_pk_bf16_f32 v37, v38, v39
	global_store_dwordx2 v[40:41], v[36:37], off offset:8
	v_cvt_pk_bf16_f32 v32, v32, v33
	v_cvt_pk_bf16_f32 v33, v34, v35
	global_store_dwordx2 v[40:41], v[32:33], off offset:264
.LBB0_1417:
	s_or_b64 exec, exec, s[40:41]
	v_cndmask_b32_e64 v250, v28, 0, vcc
	v_cndmask_b32_e64 v244, v30, 0, vcc
	v_cndmask_b32_e64 v251, v29, 0, vcc
	v_cndmask_b32_e64 v245, v31, 0, vcc
	v_cndmask_b32_e64 v220, v24, 0, vcc
	v_cndmask_b32_e64 v248, v26, 0, vcc
	v_cndmask_b32_e64 v221, v25, 0, vcc
	v_cndmask_b32_e64 v249, v27, 0, vcc
	v_pk_fma_f32 v[246:247], v[28:29], v[68:69], v[84:85]
	v_pk_fma_f32 v[240:241], v[30:31], v[70:71], v[86:87]
	v_pk_fma_f32 v[214:215], v[24:25], v[100:101], v[122:123]
	v_pk_fma_f32 v[208:209], v[26:27], v[102:103], v[124:125]
	v_fmac_f32_dpp v246, v250, v64 row_ror:1 row_mask:0xf bank_mask:0xf bound_ctrl:1
	v_fmac_f32_dpp v240, v244, v66 row_ror:1 row_mask:0xf bank_mask:0xf bound_ctrl:1
	v_fmac_f32_dpp v247, v251, v65 row_ror:1 row_mask:0xf bank_mask:0xf bound_ctrl:1
	v_fmac_f32_dpp v241, v245, v67 row_ror:1 row_mask:0xf bank_mask:0xf bound_ctrl:1
	v_fmac_f32_dpp v214, v220, v92 row_ror:1 row_mask:0xf bank_mask:0xf bound_ctrl:1
	v_fmac_f32_dpp v208, v248, v94 row_ror:1 row_mask:0xf bank_mask:0xf bound_ctrl:1
	v_fmac_f32_dpp v215, v221, v93 row_ror:1 row_mask:0xf bank_mask:0xf bound_ctrl:1
	v_fmac_f32_dpp v209, v249, v95 row_ror:1 row_mask:0xf bank_mask:0xf bound_ctrl:1
	v_cndmask_b32_e64 v250, v28, v20, s[34:35]
	v_cndmask_b32_e64 v244, v30, v22, s[34:35]
	v_cndmask_b32_e64 v251, v29, v21, s[34:35]
	v_cndmask_b32_e64 v245, v31, v23, s[34:35]
	v_cndmask_b32_e64 v220, v24, v16, s[34:35]
	v_cndmask_b32_e64 v248, v26, v18, s[34:35]
	v_cndmask_b32_e64 v221, v25, v17, s[34:35]
	v_cndmask_b32_e64 v249, v27, v19, s[34:35]
	v_fmac_f32_dpp v246, v250, v74 row_ror:15 row_mask:0xf bank_mask:0xf
	v_fmac_f32_dpp v240, v244, v76 row_ror:15 row_mask:0xf bank_mask:0xf
	v_fmac_f32_dpp v247, v251, v75 row_ror:15 row_mask:0xf bank_mask:0xf
	v_fmac_f32_dpp v241, v245, v77 row_ror:15 row_mask:0xf bank_mask:0xf
	v_fmac_f32_dpp v214, v220, v108 row_ror:15 row_mask:0xf bank_mask:0xf
	v_fmac_f32_dpp v208, v248, v110 row_ror:15 row_mask:0xf bank_mask:0xf
	v_fmac_f32_dpp v215, v221, v109 row_ror:15 row_mask:0xf bank_mask:0xf
	v_fmac_f32_dpp v209, v249, v111 row_ror:15 row_mask:0xf bank_mask:0xf
	v_pk_mul_f32 v[206:207], v[254:255], v[246:247]
	v_pk_mul_f32 v[222:223], v[254:255], v[240:241]
	v_exp_f32_e32 v206, v206
	v_exp_f32_e32 v222, v222
	v_exp_f32_e32 v207, v207
	v_exp_f32_e32 v223, v223
	v_pk_add_f32 v[206:207], v[206:207], v[252:253]
	v_pk_add_f32 v[222:223], v[222:223], v[252:253]
	v_rcp_f32_e32 v206, v206
	v_rcp_f32_e32 v222, v222
	v_rcp_f32_e32 v207, v207
	v_rcp_f32_e32 v223, v223
	v_pk_mul_f32 v[246:247], v[246:247], v[206:207]
	v_pk_mul_f32 v[240:241], v[240:241], v[222:223]
	v_pk_mul_f32 v[214:215], v[214:215], v[246:247]
	v_pk_mul_f32 v[208:209], v[208:209], v[240:241]
	s_nop 0
	s_nop 0
	s_nop 0
	s_nop 0
	v_or_b32_e32 v32, s85, v200
	s_ashr_i32 s6, s85, 8
	s_mul_hi_i32 s7, s6, 0x160000
	s_mul_i32 s6, s6, 0x160000
	v_lshlrev_b32_e32 v32, 6, v32
	s_movk_i32 s31, 0x33c0
	v_and_or_b32 v32, v32, s31, v82
	s_add_u32 s40, s86, s6
	s_addc_u32 s41, s87, s7
	v_lshlrev_b32_e32 v164, 1, v32
	v_cvt_pk_bf16_f32 v98, v214, v215
	v_cvt_pk_bf16_f32 v99, v208, v209
	global_store_dwordx4 v164, v[96:99], s[40:41]
	s_and_saveexec_b64 s[6:7], s[36:37]
	s_cbranch_execz .LBB0_1419
	v_mov_b64_e32 v[32:33], s[0:1]
	v_mad_i64_i32 v[32:33], s[36:37], v156, s66, v[32:33]
	v_lshl_add_u64 v[32:33], s[16:17], 1, v[32:33]
	s_lshl_b32 s48, s5, 1
	v_lshl_add_u64 v[32:33], v[32:33], 0, s[48:49]
	v_mov_b32_e32 v179, v165
	v_lshl_add_u64 v[32:33], v[32:33], 0, v[178:179]
	v_cvt_pk_bf16_f32 v34, v28, v29
	v_cvt_pk_bf16_f32 v35, v30, v31
	global_store_dwordx2 v[32:33], v[34:35], off offset:8
	v_cvt_pk_bf16_f32 v34, v24, v25
	v_cvt_pk_bf16_f32 v35, v26, v27
	global_store_dwordx2 v[32:33], v[34:35], off offset:264
.LBB0_1419:
	s_or_b64 exec, exec, s[6:7]
	v_cndmask_b32_e64 v242, v20, v28, vcc
	v_cndmask_b32_e64 v220, v22, v30, vcc
	v_cndmask_b32_e64 v243, v21, v29, vcc
	v_cndmask_b32_e64 v221, v23, v31, vcc
	v_cndmask_b32_e64 v210, v16, v24, vcc
	v_cndmask_b32_e64 v246, v18, v26, vcc
	v_cndmask_b32_e64 v211, v17, v25, vcc
	v_cndmask_b32_e64 v247, v19, v27, vcc
	v_pk_fma_f32 v[212:213], v[20:21], v[68:69], v[84:85]
	v_pk_fma_f32 v[206:207], v[22:23], v[70:71], v[86:87]
	v_pk_fma_f32 v[204:205], v[16:17], v[100:101], v[122:123]
	v_pk_fma_f32 v[244:245], v[18:19], v[102:103], v[124:125]
	v_fmac_f32_dpp v212, v242, v64 row_ror:1 row_mask:0xf bank_mask:0xf bound_ctrl:1
	v_fmac_f32_dpp v206, v220, v66 row_ror:1 row_mask:0xf bank_mask:0xf bound_ctrl:1
	v_fmac_f32_dpp v213, v243, v65 row_ror:1 row_mask:0xf bank_mask:0xf bound_ctrl:1
	v_fmac_f32_dpp v207, v221, v67 row_ror:1 row_mask:0xf bank_mask:0xf bound_ctrl:1
	v_fmac_f32_dpp v204, v210, v92 row_ror:1 row_mask:0xf bank_mask:0xf bound_ctrl:1
	v_fmac_f32_dpp v244, v246, v94 row_ror:1 row_mask:0xf bank_mask:0xf bound_ctrl:1
	v_fmac_f32_dpp v205, v211, v93 row_ror:1 row_mask:0xf bank_mask:0xf bound_ctrl:1
	v_fmac_f32_dpp v245, v247, v95 row_ror:1 row_mask:0xf bank_mask:0xf bound_ctrl:1
	v_cndmask_b32_e64 v242, v20, v12, s[34:35]
	v_cndmask_b32_e64 v220, v22, v14, s[34:35]
	v_cndmask_b32_e64 v243, v21, v13, s[34:35]
	v_cndmask_b32_e64 v221, v23, v15, s[34:35]
	v_cndmask_b32_e64 v210, v16, v8, s[34:35]
	v_cndmask_b32_e64 v246, v18, v10, s[34:35]
	v_cndmask_b32_e64 v211, v17, v9, s[34:35]
	v_cndmask_b32_e64 v247, v19, v11, s[34:35]
	v_fmac_f32_dpp v212, v242, v74 row_ror:15 row_mask:0xf bank_mask:0xf
	v_fmac_f32_dpp v206, v220, v76 row_ror:15 row_mask:0xf bank_mask:0xf
	v_fmac_f32_dpp v213, v243, v75 row_ror:15 row_mask:0xf bank_mask:0xf
	v_fmac_f32_dpp v207, v221, v77 row_ror:15 row_mask:0xf bank_mask:0xf
	v_fmac_f32_dpp v204, v210, v108 row_ror:15 row_mask:0xf bank_mask:0xf
	v_fmac_f32_dpp v244, v246, v110 row_ror:15 row_mask:0xf bank_mask:0xf
	v_fmac_f32_dpp v205, v211, v109 row_ror:15 row_mask:0xf bank_mask:0xf
	v_fmac_f32_dpp v245, v247, v111 row_ror:15 row_mask:0xf bank_mask:0xf
	v_pk_mul_f32 v[250:251], v[254:255], v[212:213]
	v_pk_mul_f32 v[248:249], v[254:255], v[206:207]
	v_exp_f32_e32 v250, v250
	v_exp_f32_e32 v248, v248
	v_exp_f32_e32 v251, v251
	v_exp_f32_e32 v249, v249
	v_pk_add_f32 v[250:251], v[250:251], v[252:253]
	v_pk_add_f32 v[248:249], v[248:249], v[252:253]
	v_rcp_f32_e32 v250, v250
	v_rcp_f32_e32 v248, v248
	v_rcp_f32_e32 v251, v251
	v_rcp_f32_e32 v249, v249
	v_pk_mul_f32 v[212:213], v[212:213], v[250:251]
	v_pk_mul_f32 v[206:207], v[206:207], v[248:249]
	v_pk_mul_f32 v[204:205], v[204:205], v[212:213]
	v_pk_mul_f32 v[244:245], v[244:245], v[206:207]
	s_nop 0
	s_nop 0
	s_nop 0
	v_cndmask_b32_e64 v240, v12, v20, vcc
	v_cndmask_b32_e64 v210, v14, v22, vcc
	v_cndmask_b32_e64 v241, v13, v21, vcc
	v_cndmask_b32_e64 v211, v15, v23, vcc
	v_cndmask_b32_e64 v222, v8, v16, vcc
	v_cndmask_b32_e64 v212, v10, v18, vcc
	v_cndmask_b32_e64 v223, v9, v17, vcc
	v_cndmask_b32_e64 v213, v11, v19, vcc
	v_pk_fma_f32 v[214:215], v[12:13], v[68:69], v[84:85]
	v_pk_fma_f32 v[250:251], v[14:15], v[70:71], v[86:87]
	v_pk_fma_f32 v[208:209], v[8:9], v[100:101], v[122:123]
	v_pk_fma_f32 v[220:221], v[10:11], v[102:103], v[124:125]
	v_fmac_f32_dpp v214, v240, v64 row_ror:1 row_mask:0xf bank_mask:0xf bound_ctrl:1
	v_fmac_f32_dpp v250, v210, v66 row_ror:1 row_mask:0xf bank_mask:0xf bound_ctrl:1
	v_fmac_f32_dpp v215, v241, v65 row_ror:1 row_mask:0xf bank_mask:0xf bound_ctrl:1
	v_fmac_f32_dpp v251, v211, v67 row_ror:1 row_mask:0xf bank_mask:0xf bound_ctrl:1
	v_fmac_f32_dpp v208, v222, v92 row_ror:1 row_mask:0xf bank_mask:0xf bound_ctrl:1
	v_fmac_f32_dpp v220, v212, v94 row_ror:1 row_mask:0xf bank_mask:0xf bound_ctrl:1
	v_fmac_f32_dpp v209, v223, v93 row_ror:1 row_mask:0xf bank_mask:0xf bound_ctrl:1
	v_fmac_f32_dpp v221, v213, v95 row_ror:1 row_mask:0xf bank_mask:0xf bound_ctrl:1
	v_cndmask_b32_e64 v240, v12, v4, s[34:35]
	v_cndmask_b32_e64 v210, v14, v6, s[34:35]
	v_cndmask_b32_e64 v241, v13, v5, s[34:35]
	v_cndmask_b32_e64 v211, v15, v7, s[34:35]
	v_cndmask_b32_e64 v222, v8, v0, s[34:35]
	v_cndmask_b32_e64 v212, v10, v2, s[34:35]
	v_cndmask_b32_e64 v223, v9, v1, s[34:35]
	v_cndmask_b32_e64 v213, v11, v3, s[34:35]
	v_fmac_f32_dpp v214, v240, v74 row_ror:15 row_mask:0xf bank_mask:0xf
	v_fmac_f32_dpp v250, v210, v76 row_ror:15 row_mask:0xf bank_mask:0xf
	v_fmac_f32_dpp v215, v241, v75 row_ror:15 row_mask:0xf bank_mask:0xf
	v_fmac_f32_dpp v251, v211, v77 row_ror:15 row_mask:0xf bank_mask:0xf
	v_fmac_f32_dpp v208, v222, v108 row_ror:15 row_mask:0xf bank_mask:0xf
	v_fmac_f32_dpp v220, v212, v110 row_ror:15 row_mask:0xf bank_mask:0xf
	v_fmac_f32_dpp v209, v223, v109 row_ror:15 row_mask:0xf bank_mask:0xf
	v_fmac_f32_dpp v221, v213, v111 row_ror:15 row_mask:0xf bank_mask:0xf
	v_pk_mul_f32 v[242:243], v[254:255], v[214:215]
	v_pk_mul_f32 v[246:247], v[254:255], v[250:251]
	v_exp_f32_e32 v242, v242
	v_exp_f32_e32 v246, v246
	v_exp_f32_e32 v243, v243
	v_exp_f32_e32 v247, v247
	v_pk_add_f32 v[242:243], v[242:243], v[252:253]
	v_pk_add_f32 v[246:247], v[246:247], v[252:253]
	v_rcp_f32_e32 v242, v242
	v_rcp_f32_e32 v246, v246
	v_rcp_f32_e32 v243, v243
	v_rcp_f32_e32 v247, v247
	v_pk_mul_f32 v[214:215], v[214:215], v[242:243]
	v_pk_mul_f32 v[250:251], v[250:251], v[246:247]
	v_pk_mul_f32 v[208:209], v[208:209], v[214:215]
	v_pk_mul_f32 v[220:221], v[220:221], v[250:251]
	s_nop 0
	v_cvt_pk_bf16_f32 v90, v204, v205
	s_nop 0
	s_nop 0
	v_cvt_pk_bf16_f32 v91, v244, v245
	s_nop 0
	s_nop 0
	s_nop 0
	v_cndmask_b32_e64 v206, v4, v12, vcc
	v_cndmask_b32_e64 v242, v6, v14, vcc
	v_cndmask_b32_e64 v207, v5, v13, vcc
	v_cndmask_b32_e64 v243, v7, v15, vcc
	v_cndmask_b32_e64 v248, v0, v8, vcc
	v_cndmask_b32_e64 v210, v2, v10, vcc
	v_cndmask_b32_e64 v249, v1, v9, vcc
	v_cndmask_b32_e64 v211, v3, v11, vcc
	v_pk_fma_f32 v[240:241], v[4:5], v[68:69], v[84:85]
	v_pk_fma_f32 v[212:213], v[6:7], v[70:71], v[86:87]
	v_pk_fma_f32 v[222:223], v[0:1], v[100:101], v[122:123]
	v_pk_fma_f32 v[250:251], v[2:3], v[102:103], v[124:125]
	v_fmac_f32_dpp v240, v206, v64 row_ror:1 row_mask:0xf bank_mask:0xf bound_ctrl:1
	v_fmac_f32_dpp v212, v242, v66 row_ror:1 row_mask:0xf bank_mask:0xf bound_ctrl:1
	v_fmac_f32_dpp v241, v207, v65 row_ror:1 row_mask:0xf bank_mask:0xf bound_ctrl:1
	v_fmac_f32_dpp v213, v243, v67 row_ror:1 row_mask:0xf bank_mask:0xf bound_ctrl:1
	v_fmac_f32_dpp v222, v248, v92 row_ror:1 row_mask:0xf bank_mask:0xf bound_ctrl:1
	v_fmac_f32_dpp v250, v210, v94 row_ror:1 row_mask:0xf bank_mask:0xf bound_ctrl:1
	v_fmac_f32_dpp v223, v249, v93 row_ror:1 row_mask:0xf bank_mask:0xf bound_ctrl:1
	v_fmac_f32_dpp v251, v211, v95 row_ror:1 row_mask:0xf bank_mask:0xf bound_ctrl:1
	v_cndmask_b32_e64 v206, v4, 0, s[34:35]
	v_cndmask_b32_e64 v242, v6, 0, s[34:35]
	v_cndmask_b32_e64 v207, v5, 0, s[34:35]
	v_cndmask_b32_e64 v243, v7, 0, s[34:35]
	v_cndmask_b32_e64 v248, v0, 0, s[34:35]
	v_cndmask_b32_e64 v210, v2, 0, s[34:35]
	v_cndmask_b32_e64 v249, v1, 0, s[34:35]
	v_cndmask_b32_e64 v211, v3, 0, s[34:35]
	v_fmac_f32_dpp v240, v206, v74 row_ror:15 row_mask:0xf bank_mask:0xf
	v_fmac_f32_dpp v212, v242, v76 row_ror:15 row_mask:0xf bank_mask:0xf
	v_fmac_f32_dpp v241, v207, v75 row_ror:15 row_mask:0xf bank_mask:0xf
	v_fmac_f32_dpp v213, v243, v77 row_ror:15 row_mask:0xf bank_mask:0xf
	v_fmac_f32_dpp v222, v248, v108 row_ror:15 row_mask:0xf bank_mask:0xf
	v_fmac_f32_dpp v250, v210, v110 row_ror:15 row_mask:0xf bank_mask:0xf
	v_fmac_f32_dpp v223, v249, v109 row_ror:15 row_mask:0xf bank_mask:0xf
	v_fmac_f32_dpp v251, v211, v111 row_ror:15 row_mask:0xf bank_mask:0xf
	v_pk_mul_f32 v[214:215], v[254:255], v[240:241]
	v_pk_mul_f32 v[246:247], v[254:255], v[212:213]
	v_exp_f32_e32 v214, v214
	v_exp_f32_e32 v246, v246
	v_exp_f32_e32 v215, v215
	v_exp_f32_e32 v247, v247
	v_pk_add_f32 v[214:215], v[214:215], v[252:253]
	v_pk_add_f32 v[246:247], v[246:247], v[252:253]
	v_rcp_f32_e32 v214, v214
	v_rcp_f32_e32 v246, v246
	v_rcp_f32_e32 v215, v215
	v_rcp_f32_e32 v247, v247
	v_pk_mul_f32 v[240:241], v[240:241], v[214:215]
	v_pk_mul_f32 v[212:213], v[212:213], v[246:247]
	v_pk_mul_f32 v[222:223], v[222:223], v[240:241]
	v_pk_mul_f32 v[250:251], v[250:251], v[212:213]
	v_cvt_pk_bf16_f32 v83, v220, v221
	s_nop 0
	s_nop 0
	s_nop 0
	v_lshl_add_u64 v[32:33], s[40:41], 0, v[164:165]
	s_movk_i32 s6, 0x1000
	v_cvt_pk_bf16_f32 v82, v208, v209
	v_add_co_u32_e64 v16, s[36:37], s6, v32
	s_nop 0
	s_nop 0
	v_addc_co_u32_e64 v17, s[36:37], 0, v33, s[36:37]
	global_store_dwordx4 v[32:33], v[88:91], off offset:2048
	global_store_dwordx4 v[16:17], v[80:83], off
	v_cvt_pk_bf16_f32 v74, v222, v223
	v_cvt_pk_bf16_f32 v75, v250, v251
	global_store_dwordx4 v[16:17], v[72:75], off offset:2048
	s_and_saveexec_b64 s[34:35], s[38:39]
	s_cbranch_execz .LBB0_1392
	v_mov_b32_e32 v181, v165
	v_lshl_add_u64 v[8:9], s[10:11], 0, v[180:181]
	v_mov_b64_e32 v[10:11], s[0:1]
	s_movk_i32 s10, 0x2c00
	v_mad_u64_u32 v[10:11], s[6:7], v8, s10, v[10:11]
	v_mad_i32_i24 v11, v9, s10, v11
	v_lshl_add_u64 v[8:9], s[16:17], 1, v[10:11]
	s_lshl_b32 s48, s5, 1
	v_lshl_add_u64 v[8:9], v[8:9], 0, s[48:49]
	v_mov_b32_e32 v179, v165
	s_movk_i32 s66, 0x2c00
	v_lshl_add_u64 v[8:9], v[8:9], 0, v[178:179]
	v_cvt_pk_bf16_f32 v4, v4, v5
	v_cvt_pk_bf16_f32 v5, v6, v7
	global_store_dwordx2 v[8:9], v[4:5], off offset:8
	v_cvt_pk_bf16_f32 v0, v0, v1
	v_cvt_pk_bf16_f32 v1, v2, v3
	global_store_dwordx2 v[8:9], v[0:1], off offset:264
	s_branch .LBB0_1392
